# static-priority lever A/B: removed the mid-block setprio 0/1 flip inside each 32-MFMA compute segment of the five GEMM K-loops (v123 base)
# baseline (speedup 1.0000x reference)
.LBB0_41:
	s_add_u32 s54, s52, 0xffe00080
	s_addc_u32 s55, s53, -1
	s_add_i32 s64, 0, 0x10000
	s_cmpk_eq_i32 s63, 0x7c
	s_cselect_b32 s57, s4, s55
	s_cselect_b32 s56, s5, s54
	s_cselect_b32 s55, s37, s62
	s_cselect_b32 s54, s43, s61
	s_add_i32 s66, 0, 0x14000
	v_add_u32_e32 v156, s64, v163
	v_add_u32_e32 v160, s66, v163
	ds_read_b128 v[134:137], v156
	ds_read_b128 v[138:141], v156 offset:1024
	ds_read_b128 v[152:155], v156 offset:2048
	ds_read_b128 v[156:159], v156 offset:3072
	ds_read_b128 v[166:169], v160
	ds_read_b128 v[170:173], v160 offset:1024
	ds_read_b128 v[174:177], v160 offset:2048
	ds_read_b128 v[178:181], v160 offset:3072
	v_lshl_add_u64 v[160:161], s[52:53], 0, v[150:151]
	s_add_i32 m0, s21, 0xc000
	ds_read_b128 v[182:185], v165
	ds_read_b128 v[186:189], v165 offset:1024
	ds_read_b128 v[198:201], v165 offset:2048
	ds_read_b128 v[202:205], v165 offset:3072
	ds_read_b128 v[206:209], v165 offset:4096
	ds_read_b128 v[210:213], v165 offset:5120
	ds_read_b128 v[214:217], v165 offset:6144
	ds_read_b128 v[236:239], v165 offset:7168
	global_load_lds_dwordx4 v[160:161], off
	v_lshl_add_u64 v[160:161], s[52:53], 0, v[148:149]
	s_add_i32 m0, s21, 0xe000
	s_nop 0
	global_load_lds_dwordx4 v[160:161], off
	s_waitcnt vmcnt(8)
	s_waitcnt lgkmcnt(0)
	s_barrier
	s_setprio 1
	s_waitcnt lgkmcnt(0)
	v_mfma_f32_16x16x32_bf16 v[130:133], v[134:137], v[182:185], v[130:133]
	v_mfma_f32_16x16x32_bf16 v[126:129], v[152:155], v[182:185], v[126:129]
	v_mfma_f32_16x16x32_bf16 v[114:117], v[134:137], v[198:201], v[114:117]
	v_mfma_f32_16x16x32_bf16 v[110:113], v[152:155], v[198:201], v[110:113]
	v_mfma_f32_16x16x32_bf16 v[98:101], v[134:137], v[206:209], v[98:101]
	v_mfma_f32_16x16x32_bf16 v[94:97], v[152:155], v[206:209], v[94:97]
	v_mfma_f32_16x16x32_bf16 v[82:85], v[134:137], v[214:217], v[82:85]
	v_mfma_f32_16x16x32_bf16 v[78:81], v[152:155], v[214:217], v[78:81]
	v_mfma_f32_16x16x32_bf16 v[130:133], v[138:141], v[186:189], v[130:133]
	v_mfma_f32_16x16x32_bf16 v[126:129], v[156:159], v[186:189], v[126:129]
	v_mfma_f32_16x16x32_bf16 v[114:117], v[138:141], v[202:205], v[114:117]
	v_mfma_f32_16x16x32_bf16 v[110:113], v[156:159], v[202:205], v[110:113]
	v_mfma_f32_16x16x32_bf16 v[98:101], v[138:141], v[210:213], v[98:101]
	v_mfma_f32_16x16x32_bf16 v[94:97], v[156:159], v[210:213], v[94:97]
	v_mfma_f32_16x16x32_bf16 v[82:85], v[138:141], v[236:239], v[82:85]
	v_mfma_f32_16x16x32_bf16 v[78:81], v[156:159], v[236:239], v[78:81]
	v_mfma_f32_16x16x32_bf16 v[122:125], v[166:169], v[182:185], v[122:125]
	v_mfma_f32_16x16x32_bf16 v[118:121], v[174:177], v[182:185], v[118:121]
	v_mfma_f32_16x16x32_bf16 v[106:109], v[166:169], v[198:201], v[106:109]
	v_mfma_f32_16x16x32_bf16 v[102:105], v[174:177], v[198:201], v[102:105]
	v_mfma_f32_16x16x32_bf16 v[90:93], v[166:169], v[206:209], v[90:93]
	v_mfma_f32_16x16x32_bf16 v[86:89], v[174:177], v[206:209], v[86:89]
	v_mfma_f32_16x16x32_bf16 v[74:77], v[166:169], v[214:217], v[74:77]
	v_mfma_f32_16x16x32_bf16 v[70:73], v[174:177], v[214:217], v[70:73]
	v_mfma_f32_16x16x32_bf16 v[122:125], v[170:173], v[186:189], v[122:125]
	v_mfma_f32_16x16x32_bf16 v[118:121], v[178:181], v[186:189], v[118:121]
	v_mfma_f32_16x16x32_bf16 v[106:109], v[170:173], v[202:205], v[106:109]
	v_mfma_f32_16x16x32_bf16 v[102:105], v[178:181], v[202:205], v[102:105]
	v_mfma_f32_16x16x32_bf16 v[90:93], v[170:173], v[210:213], v[90:93]
	v_mfma_f32_16x16x32_bf16 v[86:89], v[178:181], v[210:213], v[86:89]
	v_mfma_f32_16x16x32_bf16 v[74:77], v[170:173], v[236:239], v[74:77]
	v_mfma_f32_16x16x32_bf16 v[70:73], v[178:181], v[236:239], v[70:73]
	s_setprio 0
	s_barrier
	s_add_i32 s64, s64, s15
	v_lshl_add_u64 v[160:161], s[54:55], 0, v[190:191]
	s_mov_b32 m0, s64
	ds_read_b128 v[182:185], v165 offset:16384
	ds_read_b128 v[186:189], v165 offset:17408
	ds_read_b128 v[198:201], v165 offset:18432
	ds_read_b128 v[202:205], v165 offset:19456
	ds_read_b128 v[206:209], v165 offset:20480
	ds_read_b128 v[210:213], v165 offset:21504
	ds_read_b128 v[214:217], v165 offset:22528
	ds_read_b128 v[236:239], v165 offset:23552
	global_load_lds_dwordx4 v[160:161], off
	s_add_i32 m0, s64, 0x2000
	s_add_u32 s64, s54, 0x200000
	v_lshl_add_u64 v[218:219], s[54:55], 0, v[146:147]
	s_addc_u32 s65, s55, 0
	s_add_i32 s66, s66, s15
	global_load_lds_dwordx4 v[218:219], off
	v_lshl_add_u64 v[240:241], s[64:65], 0, v[190:191]
	s_mov_b32 m0, s66
	v_lshl_add_u64 v[242:243], s[56:57], 0, v[144:145]
	global_load_lds_dwordx4 v[240:241], off
	v_lshl_add_u64 v[240:241], s[64:65], 0, v[146:147]
	s_add_i32 m0, s66, 0x2000
	s_nop 0
	global_load_lds_dwordx4 v[240:241], off
	v_lshl_add_u64 v[240:241], s[56:57], 0, v[142:143]
	s_mov_b32 m0, s21
	s_nop 0
	global_load_lds_dwordx4 v[240:241], off
	s_mov_b32 m0, s23
	s_nop 0
	global_load_lds_dwordx4 v[242:243], off
	s_waitcnt vmcnt(8)
	s_waitcnt lgkmcnt(0)
	s_barrier
	s_setprio 1
	s_waitcnt lgkmcnt(0)
	v_mfma_f32_16x16x32_bf16 v[66:69], v[134:137], v[182:185], v[66:69]
	v_mfma_f32_16x16x32_bf16 v[62:65], v[152:155], v[182:185], v[62:65]
	v_mfma_f32_16x16x32_bf16 v[50:53], v[134:137], v[198:201], v[50:53]
	v_mfma_f32_16x16x32_bf16 v[46:49], v[152:155], v[198:201], v[46:49]
	v_mfma_f32_16x16x32_bf16 v[34:37], v[134:137], v[206:209], v[34:37]
	v_mfma_f32_16x16x32_bf16 v[30:33], v[152:155], v[206:209], v[30:33]
	v_mfma_f32_16x16x32_bf16 v[18:21], v[134:137], v[214:217], v[18:21]
	v_mfma_f32_16x16x32_bf16 v[14:17], v[152:155], v[214:217], v[14:17]
	v_mfma_f32_16x16x32_bf16 v[66:69], v[138:141], v[186:189], v[66:69]
	v_mfma_f32_16x16x32_bf16 v[62:65], v[156:159], v[186:189], v[62:65]
	v_mfma_f32_16x16x32_bf16 v[50:53], v[138:141], v[202:205], v[50:53]
	v_mfma_f32_16x16x32_bf16 v[46:49], v[156:159], v[202:205], v[46:49]
	v_mfma_f32_16x16x32_bf16 v[34:37], v[138:141], v[210:213], v[34:37]
	v_mfma_f32_16x16x32_bf16 v[30:33], v[156:159], v[210:213], v[30:33]
	v_mfma_f32_16x16x32_bf16 v[18:21], v[138:141], v[236:239], v[18:21]
	v_mfma_f32_16x16x32_bf16 v[14:17], v[156:159], v[236:239], v[14:17]
	v_mfma_f32_16x16x32_bf16 v[58:61], v[166:169], v[182:185], v[58:61]
	v_mfma_f32_16x16x32_bf16 v[54:57], v[174:177], v[182:185], v[54:57]
	v_mfma_f32_16x16x32_bf16 v[42:45], v[166:169], v[198:201], v[42:45]
	v_mfma_f32_16x16x32_bf16 v[38:41], v[174:177], v[198:201], v[38:41]
	v_mfma_f32_16x16x32_bf16 v[26:29], v[166:169], v[206:209], v[26:29]
	v_mfma_f32_16x16x32_bf16 v[22:25], v[174:177], v[206:209], v[22:25]
	v_mfma_f32_16x16x32_bf16 v[10:13], v[166:169], v[214:217], v[10:13]
	v_mfma_f32_16x16x32_bf16 v[6:9], v[174:177], v[214:217], v[6:9]
	v_mfma_f32_16x16x32_bf16 v[58:61], v[170:173], v[186:189], v[58:61]
	v_mfma_f32_16x16x32_bf16 v[54:57], v[178:181], v[186:189], v[54:57]
	v_mfma_f32_16x16x32_bf16 v[42:45], v[170:173], v[202:205], v[42:45]
	v_mfma_f32_16x16x32_bf16 v[38:41], v[178:181], v[202:205], v[38:41]
	v_mfma_f32_16x16x32_bf16 v[26:29], v[170:173], v[210:213], v[26:29]
	v_mfma_f32_16x16x32_bf16 v[22:25], v[178:181], v[210:213], v[22:25]
	v_mfma_f32_16x16x32_bf16 v[10:13], v[170:173], v[236:239], v[10:13]
	v_mfma_f32_16x16x32_bf16 v[6:9], v[178:181], v[236:239], v[6:9]
	s_setprio 0
	s_barrier
	s_add_i32 s64, 0, 0x18000
	s_add_i32 s65, 0, 0x1c000
	v_add_u32_e32 v156, s64, v163
	v_add_u32_e32 v178, s65, v163
	ds_read_b128 v[134:137], v156
	ds_read_b128 v[138:141], v156 offset:1024
	ds_read_b128 v[152:155], v156 offset:2048
	ds_read_b128 v[156:159], v156 offset:3072
	ds_read_b128 v[166:169], v178
	ds_read_b128 v[170:173], v178 offset:1024
	ds_read_b128 v[174:177], v178 offset:2048
	ds_read_b128 v[178:181], v178 offset:3072
	s_add_u32 s56, s56, 0x200000
	s_addc_u32 s57, s57, 0
	s_mov_b32 m0, s26
	v_lshl_add_u64 v[244:245], s[56:57], 0, v[142:143]
	ds_read_b128 v[182:185], v165 offset:32768
	ds_read_b128 v[186:189], v165 offset:33792
	ds_read_b128 v[198:201], v165 offset:34816
	ds_read_b128 v[202:205], v165 offset:35840
	ds_read_b128 v[206:209], v165 offset:36864
	ds_read_b128 v[210:213], v165 offset:37888
	ds_read_b128 v[214:217], v165 offset:38912
	ds_read_b128 v[236:239], v165 offset:39936
	global_load_lds_dwordx4 v[244:245], off
	v_lshl_add_u64 v[244:245], s[56:57], 0, v[144:145]
	s_mov_b32 m0, s29
	s_nop 0
	global_load_lds_dwordx4 v[244:245], off
	s_waitcnt vmcnt(8)
	s_waitcnt lgkmcnt(0)
	s_barrier
	s_setprio 1
	s_waitcnt lgkmcnt(0)
	v_mfma_f32_16x16x32_bf16 v[130:133], v[134:137], v[182:185], v[130:133]
	v_mfma_f32_16x16x32_bf16 v[126:129], v[152:155], v[182:185], v[126:129]
	v_mfma_f32_16x16x32_bf16 v[114:117], v[134:137], v[198:201], v[114:117]
	v_mfma_f32_16x16x32_bf16 v[110:113], v[152:155], v[198:201], v[110:113]
	v_mfma_f32_16x16x32_bf16 v[98:101], v[134:137], v[206:209], v[98:101]
	v_mfma_f32_16x16x32_bf16 v[94:97], v[152:155], v[206:209], v[94:97]
	v_mfma_f32_16x16x32_bf16 v[82:85], v[134:137], v[214:217], v[82:85]
	v_mfma_f32_16x16x32_bf16 v[78:81], v[152:155], v[214:217], v[78:81]
	v_mfma_f32_16x16x32_bf16 v[130:133], v[138:141], v[186:189], v[130:133]
	v_mfma_f32_16x16x32_bf16 v[126:129], v[156:159], v[186:189], v[126:129]
	v_mfma_f32_16x16x32_bf16 v[114:117], v[138:141], v[202:205], v[114:117]
	v_mfma_f32_16x16x32_bf16 v[110:113], v[156:159], v[202:205], v[110:113]
	v_mfma_f32_16x16x32_bf16 v[98:101], v[138:141], v[210:213], v[98:101]
	v_mfma_f32_16x16x32_bf16 v[94:97], v[156:159], v[210:213], v[94:97]
	v_mfma_f32_16x16x32_bf16 v[82:85], v[138:141], v[236:239], v[82:85]
	v_mfma_f32_16x16x32_bf16 v[78:81], v[156:159], v[236:239], v[78:81]
	v_mfma_f32_16x16x32_bf16 v[122:125], v[166:169], v[182:185], v[122:125]
	v_mfma_f32_16x16x32_bf16 v[118:121], v[174:177], v[182:185], v[118:121]
	v_mfma_f32_16x16x32_bf16 v[106:109], v[166:169], v[198:201], v[106:109]
	v_mfma_f32_16x16x32_bf16 v[102:105], v[174:177], v[198:201], v[102:105]
	v_mfma_f32_16x16x32_bf16 v[90:93], v[166:169], v[206:209], v[90:93]
	v_mfma_f32_16x16x32_bf16 v[86:89], v[174:177], v[206:209], v[86:89]
	v_mfma_f32_16x16x32_bf16 v[74:77], v[166:169], v[214:217], v[74:77]
	v_mfma_f32_16x16x32_bf16 v[70:73], v[174:177], v[214:217], v[70:73]
	v_mfma_f32_16x16x32_bf16 v[122:125], v[170:173], v[186:189], v[122:125]
	v_mfma_f32_16x16x32_bf16 v[118:121], v[178:181], v[186:189], v[118:121]
	v_mfma_f32_16x16x32_bf16 v[106:109], v[170:173], v[202:205], v[106:109]
	v_mfma_f32_16x16x32_bf16 v[102:105], v[178:181], v[202:205], v[102:105]
	v_mfma_f32_16x16x32_bf16 v[90:93], v[170:173], v[210:213], v[90:93]
	v_mfma_f32_16x16x32_bf16 v[86:89], v[178:181], v[210:213], v[86:89]
	v_mfma_f32_16x16x32_bf16 v[74:77], v[170:173], v[236:239], v[74:77]
	v_mfma_f32_16x16x32_bf16 v[70:73], v[178:181], v[236:239], v[70:73]
	s_setprio 0
	s_barrier
	s_add_i32 s56, s64, s15
	v_lshl_add_u64 v[160:161], v[160:161], 0, s[30:31]
	s_mov_b32 m0, s56
	ds_read_b128 v[182:185], v165 offset:49152
	ds_read_b128 v[186:189], v165 offset:50176
	ds_read_b128 v[198:201], v165 offset:51200
	ds_read_b128 v[202:205], v165 offset:52224
	ds_read_b128 v[206:209], v165 offset:53248
	ds_read_b128 v[210:213], v165 offset:54272
	ds_read_b128 v[214:217], v165 offset:55296
	ds_read_b128 v[236:239], v165 offset:56320
	global_load_lds_dwordx4 v[160:161], off
	s_add_i32 m0, s56, 0x2000
	s_add_u32 s54, s54, 0x200080
	v_lshl_add_u64 v[160:161], v[218:219], 0, s[30:31]
	s_addc_u32 s55, s55, 0
	s_add_i32 s56, s65, s15
	global_load_lds_dwordx4 v[160:161], off
	v_lshl_add_u64 v[160:161], s[54:55], 0, v[190:191]
	s_mov_b32 m0, s56
	s_nop 0
	global_load_lds_dwordx4 v[160:161], off
	v_lshl_add_u64 v[160:161], s[54:55], 0, v[146:147]
	s_add_i32 m0, s56, 0x2000
	s_nop 0
	global_load_lds_dwordx4 v[160:161], off
	v_lshl_add_u64 v[160:161], v[240:241], 0, s[30:31]
	s_mov_b32 m0, s51
	s_nop 0
	global_load_lds_dwordx4 v[160:161], off
	v_lshl_add_u64 v[160:161], v[242:243], 0, s[30:31]
	s_mov_b32 m0, s58
	s_nop 0
	global_load_lds_dwordx4 v[160:161], off
	s_waitcnt vmcnt(8)
	s_waitcnt lgkmcnt(0)
	s_barrier
	s_setprio 1
	s_waitcnt lgkmcnt(0)
	v_mfma_f32_16x16x32_bf16 v[66:69], v[134:137], v[182:185], v[66:69]
	v_mfma_f32_16x16x32_bf16 v[62:65], v[152:155], v[182:185], v[62:65]
	v_mfma_f32_16x16x32_bf16 v[50:53], v[134:137], v[198:201], v[50:53]
	v_mfma_f32_16x16x32_bf16 v[46:49], v[152:155], v[198:201], v[46:49]
	v_mfma_f32_16x16x32_bf16 v[34:37], v[134:137], v[206:209], v[34:37]
	v_mfma_f32_16x16x32_bf16 v[30:33], v[152:155], v[206:209], v[30:33]
	v_mfma_f32_16x16x32_bf16 v[18:21], v[134:137], v[214:217], v[18:21]
	v_mfma_f32_16x16x32_bf16 v[14:17], v[152:155], v[214:217], v[14:17]
	v_mfma_f32_16x16x32_bf16 v[66:69], v[138:141], v[186:189], v[66:69]
	v_mfma_f32_16x16x32_bf16 v[62:65], v[156:159], v[186:189], v[62:65]
	v_mfma_f32_16x16x32_bf16 v[50:53], v[138:141], v[202:205], v[50:53]
	v_mfma_f32_16x16x32_bf16 v[46:49], v[156:159], v[202:205], v[46:49]
	v_mfma_f32_16x16x32_bf16 v[34:37], v[138:141], v[210:213], v[34:37]
	v_mfma_f32_16x16x32_bf16 v[30:33], v[156:159], v[210:213], v[30:33]
	v_mfma_f32_16x16x32_bf16 v[18:21], v[138:141], v[236:239], v[18:21]
	v_mfma_f32_16x16x32_bf16 v[14:17], v[156:159], v[236:239], v[14:17]
	v_mfma_f32_16x16x32_bf16 v[58:61], v[166:169], v[182:185], v[58:61]
	v_mfma_f32_16x16x32_bf16 v[54:57], v[174:177], v[182:185], v[54:57]
	v_mfma_f32_16x16x32_bf16 v[42:45], v[166:169], v[198:201], v[42:45]
	v_mfma_f32_16x16x32_bf16 v[38:41], v[174:177], v[198:201], v[38:41]
	v_mfma_f32_16x16x32_bf16 v[26:29], v[166:169], v[206:209], v[26:29]
	v_mfma_f32_16x16x32_bf16 v[22:25], v[174:177], v[206:209], v[22:25]
	v_mfma_f32_16x16x32_bf16 v[10:13], v[166:169], v[214:217], v[10:13]
	v_mfma_f32_16x16x32_bf16 v[6:9], v[174:177], v[214:217], v[6:9]
	v_mfma_f32_16x16x32_bf16 v[58:61], v[170:173], v[186:189], v[58:61]
	v_mfma_f32_16x16x32_bf16 v[54:57], v[178:181], v[186:189], v[54:57]
	v_mfma_f32_16x16x32_bf16 v[42:45], v[170:173], v[202:205], v[42:45]
	v_mfma_f32_16x16x32_bf16 v[38:41], v[178:181], v[202:205], v[38:41]
	v_mfma_f32_16x16x32_bf16 v[26:29], v[170:173], v[210:213], v[26:29]
	v_mfma_f32_16x16x32_bf16 v[22:25], v[178:181], v[210:213], v[22:25]
	v_mfma_f32_16x16x32_bf16 v[10:13], v[170:173], v[236:239], v[10:13]
	v_mfma_f32_16x16x32_bf16 v[6:9], v[178:181], v[236:239], v[6:9]
	s_setprio 0
	s_barrier
	s_add_i32 s63, s63, 2
	s_add_u32 s61, s61, 0x100
	s_addc_u32 s62, s62, 0
	s_add_u32 s52, s52, 0x100
	s_addc_u32 s53, s53, 0
	s_cmpk_gt_u32 s63, 0x7d
	s_cbranch_scc0 .LBB0_41
	v_lshl_or_b32 v152, s50, 8, v164
	v_lshl_add_u32 v154, s48, 8, v162
	v_ashrrev_i32_e32 v153, 31, v152
	v_readlane_b32 s4, v255, 14
	v_ashrrev_i32_e32 v155, 31, v154
	v_lshlrev_b64 v[176:177], 1, v[152:153]
	v_readlane_b32 s5, v255, 15
	v_lshlrev_b64 v[158:159], 12, v[154:155]
	v_or_b32_e32 v160, 16, v154
	v_lshl_add_u64 v[156:157], s[4:5], 0, v[176:177]
	v_lshl_add_u64 v[134:135], v[156:157], 0, v[158:159]
	global_load_dwordx4 v[168:171], v[134:135], off
	global_load_dwordx4 v[172:175], v[134:135], off offset:256
	v_ashrrev_i32_e32 v161, 31, v160
	v_lshlrev_b64 v[134:135], 12, v[160:161]
	v_lshl_add_u64 v[134:135], v[156:157], 0, v[134:135]
	global_load_dwordx4 v[138:141], v[134:135], off
	s_nop 0
	global_load_dwordx4 v[134:137], v[134:135], off offset:256
	v_and_b32_e32 v167, 64, v221
	v_xor_b32_e32 v166, 16, v221
	v_add_u32_e32 v167, 64, v167
	v_xor_b32_e32 v178, 32, v221
	v_cmp_lt_i32_e32 vcc, v166, v167
	s_waitcnt vmcnt(0)
	v_lshlrev_b32_e32 v180, 16, v170
	v_cndmask_b32_e32 v166, v221, v166, vcc
	v_cmp_lt_i32_e32 vcc, v178, v167
	v_and_b32_e32 v181, 0xffff0000, v170
	v_lshlrev_b32_e32 v170, 16, v171
	v_cndmask_b32_e32 v167, v221, v178, vcc
	v_lshl_add_u64 v[178:179], s[4:5], 0, v[158:159]
	v_lshl_add_u64 v[176:177], v[178:179], 0, v[176:177]
	v_lshlrev_b32_e32 v178, 16, v168
	v_and_b32_e32 v179, 0xffff0000, v168
	v_lshlrev_b32_e32 v168, 16, v169
	v_and_b32_e32 v169, 0xffff0000, v169
	v_and_b32_e32 v171, 0xffff0000, v171
	v_lshlrev_b32_e32 v182, 16, v172
	v_and_b32_e32 v183, 0xffff0000, v172
	v_lshlrev_b32_e32 v172, 16, v173
	v_and_b32_e32 v173, 0xffff0000, v173
	v_lshlrev_b32_e32 v184, 16, v174
	v_and_b32_e32 v185, 0xffff0000, v174
	v_lshlrev_b32_e32 v174, 16, v175
	v_and_b32_e32 v175, 0xffff0000, v175
	v_pk_add_f32 v[132:133], v[132:133], v[168:169]
	v_pk_add_f32 v[130:131], v[130:131], v[178:179]
	v_pk_add_f32 v[128:129], v[128:129], v[170:171]
	v_pk_add_f32 v[126:127], v[126:127], v[180:181]
	v_pk_add_f32 v[168:169], v[124:125], v[172:173]
	v_pk_add_f32 v[122:123], v[122:123], v[182:183]
	v_pk_add_f32 v[170:171], v[120:121], v[174:175]
	v_pk_add_f32 v[172:173], v[118:119], v[184:185]
	v_mul_f32_e32 v121, v131, v131
	v_mul_f32_e32 v124, v133, v133
	v_mul_f32_e32 v125, v127, v127
	v_mul_f32_e32 v174, v129, v129
	v_cvt_pk_bf16_f32 v118, v130, v131
	v_cvt_pk_bf16_f32 v119, v132, v133
	v_cvt_pk_bf16_f32 v120, v126, v127
	v_mul_f32_e32 v127, v123, v123
	v_mul_f32_e32 v131, v169, v169
	v_mul_f32_e32 v133, v173, v173
	v_mul_f32_e32 v175, v171, v171
	v_fmac_f32_e32 v121, v130, v130
	v_fmac_f32_e32 v124, v132, v132
	v_fmac_f32_e32 v125, v126, v126
	v_fmac_f32_e32 v174, v128, v128
	v_fmac_f32_e32 v127, v122, v122
	v_fmac_f32_e32 v131, v168, v168
	v_fmac_f32_e32 v133, v172, v172
	v_fmac_f32_e32 v175, v170, v170
	v_add_f32_e32 v121, v121, v124
	v_add_f32_e32 v124, v125, v174
	v_add_f32_e32 v125, v127, v131
	v_add_f32_e32 v126, v133, v175
	v_add_f32_e32 v121, v121, v124
	v_add_f32_e32 v124, v125, v126
	v_lshlrev_b32_e32 v166, 2, v166
	v_add_f32_e32 v126, v121, v124
	ds_bpermute_b32 v127, v166, v126
	v_cvt_pk_bf16_f32 v121, v128, v129
	global_store_dwordx4 v[176:177], v[118:121], off
	v_cvt_pk_bf16_f32 v124, v122, v123
	v_cvt_pk_bf16_f32 v125, v168, v169
	s_waitcnt lgkmcnt(0)
	s_nop 0
	v_add_f32_e32 v121, v126, v127
	v_lshlrev_b32_e32 v120, 2, v167
	ds_bpermute_b32 v122, v120, v121
	v_lshl_add_u64 v[118:119], v[154:155], 3, s[18:19]
	v_cvt_pk_bf16_f32 v126, v172, v173
	v_cvt_pk_bf16_f32 v127, v170, v171
	global_store_dwordx4 v[176:177], v[124:127], off offset:256
	s_and_saveexec_b64 s[4:5], s[38:39]
	s_cbranch_execz .LBB0_44
	s_waitcnt lgkmcnt(0)
	v_add_f32_e32 v121, v121, v122
	v_mul_f32_e32 v121, 0x4b800000, v121
	v_trunc_f32_e32 v121, v121
	v_mul_f32_e32 v122, 0x2f800000, v121
	v_floor_f32_e32 v123, v122
	v_fmac_f32_e32 v121, 0xcf800000, v123
	v_cvt_u32_f32_e32 v122, v121
	v_cvt_u32_f32_e32 v123, v123
	global_atomic_add_x2 v[118:119], v[122:123], off

.LBB0_80:
	s_add_u32 s56, s54, 0xfff80080
	s_addc_u32 s57, s55, -1
	s_add_i32 s65, 0, 0x10000
	s_cmp_eq_u32 s64, 28
	s_cselect_b32 s59, s4, s57
	s_cselect_b32 s58, s5, s56
	s_cselect_b32 s57, s45, s63
	s_cselect_b32 s56, s47, s62
	s_add_i32 s68, 0, 0x14000
	v_add_u32_e32 v156, s65, v169
	v_add_u32_e32 v176, s68, v169
	ds_read_b128 v[144:147], v156
	ds_read_b128 v[148:151], v156 offset:1024
	ds_read_b128 v[152:155], v156 offset:2048
	ds_read_b128 v[156:159], v156 offset:3072
	ds_read_b128 v[160:163], v176
	ds_read_b128 v[164:167], v176 offset:1024
	ds_read_b128 v[172:175], v176 offset:2048
	ds_read_b128 v[176:179], v176 offset:3072
	v_lshl_add_u64 v[188:189], s[54:55], 0, v[142:143]
	s_add_i32 m0, s14, 0xc000
	ds_read_b128 v[180:183], v171
	ds_read_b128 v[184:187], v171 offset:1024
	ds_read_b128 v[198:201], v171 offset:2048
	ds_read_b128 v[202:205], v171 offset:3072
	ds_read_b128 v[206:209], v171 offset:4096
	ds_read_b128 v[210:213], v171 offset:5120
	ds_read_b128 v[214:217], v171 offset:6144
	ds_read_b128 v[236:239], v171 offset:7168
	global_load_lds_dwordx4 v[188:189], off
	v_lshl_add_u64 v[188:189], s[54:55], 0, v[140:141]
	s_add_i32 m0, s14, 0xe000
	s_nop 0
	global_load_lds_dwordx4 v[188:189], off
	s_waitcnt vmcnt(8)
	s_waitcnt lgkmcnt(0)
	s_barrier
	s_setprio 1
	s_waitcnt lgkmcnt(0)
	v_mfma_f32_16x16x32_bf16 v[130:133], v[144:147], v[180:183], v[130:133]
	v_mfma_f32_16x16x32_bf16 v[126:129], v[152:155], v[180:183], v[126:129]
	v_mfma_f32_16x16x32_bf16 v[114:117], v[144:147], v[198:201], v[114:117]
	v_mfma_f32_16x16x32_bf16 v[110:113], v[152:155], v[198:201], v[110:113]
	v_mfma_f32_16x16x32_bf16 v[98:101], v[144:147], v[206:209], v[98:101]
	v_mfma_f32_16x16x32_bf16 v[94:97], v[152:155], v[206:209], v[94:97]
	v_mfma_f32_16x16x32_bf16 v[82:85], v[144:147], v[214:217], v[82:85]
	v_mfma_f32_16x16x32_bf16 v[78:81], v[152:155], v[214:217], v[78:81]
	v_mfma_f32_16x16x32_bf16 v[130:133], v[148:151], v[184:187], v[130:133]
	v_mfma_f32_16x16x32_bf16 v[126:129], v[156:159], v[184:187], v[126:129]
	v_mfma_f32_16x16x32_bf16 v[114:117], v[148:151], v[202:205], v[114:117]
	v_mfma_f32_16x16x32_bf16 v[110:113], v[156:159], v[202:205], v[110:113]
	v_mfma_f32_16x16x32_bf16 v[98:101], v[148:151], v[210:213], v[98:101]
	v_mfma_f32_16x16x32_bf16 v[94:97], v[156:159], v[210:213], v[94:97]
	v_mfma_f32_16x16x32_bf16 v[82:85], v[148:151], v[236:239], v[82:85]
	v_mfma_f32_16x16x32_bf16 v[78:81], v[156:159], v[236:239], v[78:81]
	v_mfma_f32_16x16x32_bf16 v[122:125], v[160:163], v[180:183], v[122:125]
	v_mfma_f32_16x16x32_bf16 v[118:121], v[172:175], v[180:183], v[118:121]
	v_mfma_f32_16x16x32_bf16 v[106:109], v[160:163], v[198:201], v[106:109]
	v_mfma_f32_16x16x32_bf16 v[102:105], v[172:175], v[198:201], v[102:105]
	v_mfma_f32_16x16x32_bf16 v[90:93], v[160:163], v[206:209], v[90:93]
	v_mfma_f32_16x16x32_bf16 v[86:89], v[172:175], v[206:209], v[86:89]
	v_mfma_f32_16x16x32_bf16 v[74:77], v[160:163], v[214:217], v[74:77]
	v_mfma_f32_16x16x32_bf16 v[70:73], v[172:175], v[214:217], v[70:73]
	v_mfma_f32_16x16x32_bf16 v[122:125], v[164:167], v[184:187], v[122:125]
	v_mfma_f32_16x16x32_bf16 v[118:121], v[176:179], v[184:187], v[118:121]
	v_mfma_f32_16x16x32_bf16 v[106:109], v[164:167], v[202:205], v[106:109]
	v_mfma_f32_16x16x32_bf16 v[102:105], v[176:179], v[202:205], v[102:105]
	v_mfma_f32_16x16x32_bf16 v[90:93], v[164:167], v[210:213], v[90:93]
	v_mfma_f32_16x16x32_bf16 v[86:89], v[176:179], v[210:213], v[86:89]
	v_mfma_f32_16x16x32_bf16 v[74:77], v[164:167], v[236:239], v[74:77]
	v_mfma_f32_16x16x32_bf16 v[70:73], v[176:179], v[236:239], v[70:73]
	s_setprio 0
	s_barrier
	s_add_i32 s65, s65, s3
	v_lshl_add_u64 v[188:189], s[56:57], 0, v[190:191]
	s_mov_b32 m0, s65
	ds_read_b128 v[180:183], v171 offset:16384
	ds_read_b128 v[184:187], v171 offset:17408
	ds_read_b128 v[198:201], v171 offset:18432
	ds_read_b128 v[202:205], v171 offset:19456
	ds_read_b128 v[206:209], v171 offset:20480
	ds_read_b128 v[210:213], v171 offset:21504
	ds_read_b128 v[214:217], v171 offset:22528
	ds_read_b128 v[236:239], v171 offset:23552
	global_load_lds_dwordx4 v[188:189], off
	s_add_i32 m0, s65, 0x2000
	s_add_u32 s66, s56, 0x80000
	v_lshl_add_u64 v[218:219], s[56:57], 0, v[138:139]
	s_addc_u32 s67, s57, 0
	s_add_i32 s65, s68, s3
	global_load_lds_dwordx4 v[218:219], off
	v_lshl_add_u64 v[240:241], s[66:67], 0, v[190:191]
	s_mov_b32 m0, s65
	v_lshl_add_u64 v[242:243], s[58:59], 0, v[136:137]
	global_load_lds_dwordx4 v[240:241], off
	v_lshl_add_u64 v[240:241], s[66:67], 0, v[138:139]
	s_add_i32 m0, s65, 0x2000
	s_nop 0
	global_load_lds_dwordx4 v[240:241], off
	v_lshl_add_u64 v[240:241], s[58:59], 0, v[134:135]
	s_mov_b32 m0, s14
	s_nop 0
	global_load_lds_dwordx4 v[240:241], off
	s_mov_b32 m0, s15
	s_nop 0
	global_load_lds_dwordx4 v[242:243], off
	s_waitcnt vmcnt(8)
	s_waitcnt lgkmcnt(0)
	s_barrier
	s_setprio 1
	s_waitcnt lgkmcnt(0)
	v_mfma_f32_16x16x32_bf16 v[66:69], v[144:147], v[180:183], v[66:69]
	v_mfma_f32_16x16x32_bf16 v[62:65], v[152:155], v[180:183], v[62:65]
	v_mfma_f32_16x16x32_bf16 v[50:53], v[144:147], v[198:201], v[50:53]
	v_mfma_f32_16x16x32_bf16 v[46:49], v[152:155], v[198:201], v[46:49]
	v_mfma_f32_16x16x32_bf16 v[34:37], v[144:147], v[206:209], v[34:37]
	v_mfma_f32_16x16x32_bf16 v[30:33], v[152:155], v[206:209], v[30:33]
	v_mfma_f32_16x16x32_bf16 v[18:21], v[144:147], v[214:217], v[18:21]
	v_mfma_f32_16x16x32_bf16 v[14:17], v[152:155], v[214:217], v[14:17]
	v_mfma_f32_16x16x32_bf16 v[66:69], v[148:151], v[184:187], v[66:69]
	v_mfma_f32_16x16x32_bf16 v[62:65], v[156:159], v[184:187], v[62:65]
	v_mfma_f32_16x16x32_bf16 v[50:53], v[148:151], v[202:205], v[50:53]
	v_mfma_f32_16x16x32_bf16 v[46:49], v[156:159], v[202:205], v[46:49]
	v_mfma_f32_16x16x32_bf16 v[34:37], v[148:151], v[210:213], v[34:37]
	v_mfma_f32_16x16x32_bf16 v[30:33], v[156:159], v[210:213], v[30:33]
	v_mfma_f32_16x16x32_bf16 v[18:21], v[148:151], v[236:239], v[18:21]
	v_mfma_f32_16x16x32_bf16 v[14:17], v[156:159], v[236:239], v[14:17]
	v_mfma_f32_16x16x32_bf16 v[58:61], v[160:163], v[180:183], v[58:61]
	v_mfma_f32_16x16x32_bf16 v[54:57], v[172:175], v[180:183], v[54:57]
	v_mfma_f32_16x16x32_bf16 v[42:45], v[160:163], v[198:201], v[42:45]
	v_mfma_f32_16x16x32_bf16 v[38:41], v[172:175], v[198:201], v[38:41]
	v_mfma_f32_16x16x32_bf16 v[26:29], v[160:163], v[206:209], v[26:29]
	v_mfma_f32_16x16x32_bf16 v[22:25], v[172:175], v[206:209], v[22:25]
	v_mfma_f32_16x16x32_bf16 v[10:13], v[160:163], v[214:217], v[10:13]
	v_mfma_f32_16x16x32_bf16 v[6:9], v[172:175], v[214:217], v[6:9]
	v_mfma_f32_16x16x32_bf16 v[58:61], v[164:167], v[184:187], v[58:61]
	v_mfma_f32_16x16x32_bf16 v[54:57], v[176:179], v[184:187], v[54:57]
	v_mfma_f32_16x16x32_bf16 v[42:45], v[164:167], v[202:205], v[42:45]
	v_mfma_f32_16x16x32_bf16 v[38:41], v[176:179], v[202:205], v[38:41]
	v_mfma_f32_16x16x32_bf16 v[26:29], v[164:167], v[210:213], v[26:29]
	v_mfma_f32_16x16x32_bf16 v[22:25], v[176:179], v[210:213], v[22:25]
	v_mfma_f32_16x16x32_bf16 v[10:13], v[164:167], v[236:239], v[10:13]
	v_mfma_f32_16x16x32_bf16 v[6:9], v[176:179], v[236:239], v[6:9]
	s_setprio 0
	s_barrier
	s_add_i32 s65, 0, 0x18000
	s_add_i32 s66, 0, 0x1c000
	v_add_u32_e32 v156, s65, v169
	v_add_u32_e32 v176, s66, v169
	ds_read_b128 v[144:147], v156
	ds_read_b128 v[148:151], v156 offset:1024
	ds_read_b128 v[152:155], v156 offset:2048
	ds_read_b128 v[156:159], v156 offset:3072
	ds_read_b128 v[160:163], v176
	ds_read_b128 v[164:167], v176 offset:1024
	ds_read_b128 v[172:175], v176 offset:2048
	ds_read_b128 v[176:179], v176 offset:3072
	s_add_u32 s58, s58, 0x80000
	s_addc_u32 s59, s59, 0
	s_mov_b32 m0, s21
	v_lshl_add_u64 v[244:245], s[58:59], 0, v[134:135]
	ds_read_b128 v[180:183], v171 offset:32768
	ds_read_b128 v[184:187], v171 offset:33792
	ds_read_b128 v[198:201], v171 offset:34816
	ds_read_b128 v[202:205], v171 offset:35840
	ds_read_b128 v[206:209], v171 offset:36864
	ds_read_b128 v[210:213], v171 offset:37888
	ds_read_b128 v[214:217], v171 offset:38912
	ds_read_b128 v[236:239], v171 offset:39936
	global_load_lds_dwordx4 v[244:245], off
	v_lshl_add_u64 v[244:245], s[58:59], 0, v[136:137]
	s_mov_b32 m0, s23
	s_nop 0
	global_load_lds_dwordx4 v[244:245], off
	s_waitcnt vmcnt(8)
	s_waitcnt lgkmcnt(0)
	s_barrier
	s_setprio 1
	s_waitcnt lgkmcnt(0)
	v_mfma_f32_16x16x32_bf16 v[130:133], v[144:147], v[180:183], v[130:133]
	v_mfma_f32_16x16x32_bf16 v[126:129], v[152:155], v[180:183], v[126:129]
	v_mfma_f32_16x16x32_bf16 v[114:117], v[144:147], v[198:201], v[114:117]
	v_mfma_f32_16x16x32_bf16 v[110:113], v[152:155], v[198:201], v[110:113]
	v_mfma_f32_16x16x32_bf16 v[98:101], v[144:147], v[206:209], v[98:101]
	v_mfma_f32_16x16x32_bf16 v[94:97], v[152:155], v[206:209], v[94:97]
	v_mfma_f32_16x16x32_bf16 v[82:85], v[144:147], v[214:217], v[82:85]
	v_mfma_f32_16x16x32_bf16 v[78:81], v[152:155], v[214:217], v[78:81]
	v_mfma_f32_16x16x32_bf16 v[130:133], v[148:151], v[184:187], v[130:133]
	v_mfma_f32_16x16x32_bf16 v[126:129], v[156:159], v[184:187], v[126:129]
	v_mfma_f32_16x16x32_bf16 v[114:117], v[148:151], v[202:205], v[114:117]
	v_mfma_f32_16x16x32_bf16 v[110:113], v[156:159], v[202:205], v[110:113]
	v_mfma_f32_16x16x32_bf16 v[98:101], v[148:151], v[210:213], v[98:101]
	v_mfma_f32_16x16x32_bf16 v[94:97], v[156:159], v[210:213], v[94:97]
	v_mfma_f32_16x16x32_bf16 v[82:85], v[148:151], v[236:239], v[82:85]
	v_mfma_f32_16x16x32_bf16 v[78:81], v[156:159], v[236:239], v[78:81]
	v_mfma_f32_16x16x32_bf16 v[122:125], v[160:163], v[180:183], v[122:125]
	v_mfma_f32_16x16x32_bf16 v[118:121], v[172:175], v[180:183], v[118:121]
	v_mfma_f32_16x16x32_bf16 v[106:109], v[160:163], v[198:201], v[106:109]
	v_mfma_f32_16x16x32_bf16 v[102:105], v[172:175], v[198:201], v[102:105]
	v_mfma_f32_16x16x32_bf16 v[90:93], v[160:163], v[206:209], v[90:93]
	v_mfma_f32_16x16x32_bf16 v[86:89], v[172:175], v[206:209], v[86:89]
	v_mfma_f32_16x16x32_bf16 v[74:77], v[160:163], v[214:217], v[74:77]
	v_mfma_f32_16x16x32_bf16 v[70:73], v[172:175], v[214:217], v[70:73]
	v_mfma_f32_16x16x32_bf16 v[122:125], v[164:167], v[184:187], v[122:125]
	v_mfma_f32_16x16x32_bf16 v[118:121], v[176:179], v[184:187], v[118:121]
	v_mfma_f32_16x16x32_bf16 v[106:109], v[164:167], v[202:205], v[106:109]
	v_mfma_f32_16x16x32_bf16 v[102:105], v[176:179], v[202:205], v[102:105]
	v_mfma_f32_16x16x32_bf16 v[90:93], v[164:167], v[210:213], v[90:93]
	v_mfma_f32_16x16x32_bf16 v[86:89], v[176:179], v[210:213], v[86:89]
	v_mfma_f32_16x16x32_bf16 v[74:77], v[164:167], v[236:239], v[74:77]
	v_mfma_f32_16x16x32_bf16 v[70:73], v[176:179], v[236:239], v[70:73]
	s_setprio 0
	s_barrier
	s_add_i32 s58, s65, s3
	v_lshl_add_u64 v[188:189], v[188:189], 0, s[30:31]
	s_mov_b32 m0, s58
	ds_read_b128 v[180:183], v171 offset:49152
	ds_read_b128 v[184:187], v171 offset:50176
	ds_read_b128 v[198:201], v171 offset:51200
	ds_read_b128 v[202:205], v171 offset:52224
	ds_read_b128 v[206:209], v171 offset:53248
	ds_read_b128 v[210:213], v171 offset:54272
	ds_read_b128 v[214:217], v171 offset:55296
	ds_read_b128 v[236:239], v171 offset:56320
	global_load_lds_dwordx4 v[188:189], off
	s_add_i32 m0, s58, 0x2000
	s_add_u32 s56, s56, 0x80080
	v_lshl_add_u64 v[188:189], v[218:219], 0, s[30:31]
	s_addc_u32 s57, s57, 0
	s_add_i32 s58, s66, s3
	global_load_lds_dwordx4 v[188:189], off
	v_lshl_add_u64 v[188:189], s[56:57], 0, v[190:191]
	s_mov_b32 m0, s58
	s_nop 0
	global_load_lds_dwordx4 v[188:189], off
	v_lshl_add_u64 v[188:189], s[56:57], 0, v[138:139]
	s_add_i32 m0, s58, 0x2000
	s_nop 0
	global_load_lds_dwordx4 v[188:189], off
	v_lshl_add_u64 v[188:189], v[240:241], 0, s[30:31]
	s_mov_b32 m0, s26
	s_nop 0
	global_load_lds_dwordx4 v[188:189], off
	v_lshl_add_u64 v[188:189], v[242:243], 0, s[30:31]
	s_mov_b32 m0, s29
	s_nop 0
	global_load_lds_dwordx4 v[188:189], off
	s_waitcnt vmcnt(8)
	s_waitcnt lgkmcnt(0)
	s_barrier
	s_setprio 1
	s_waitcnt lgkmcnt(0)
	v_mfma_f32_16x16x32_bf16 v[66:69], v[144:147], v[180:183], v[66:69]
	v_mfma_f32_16x16x32_bf16 v[62:65], v[152:155], v[180:183], v[62:65]
	v_mfma_f32_16x16x32_bf16 v[50:53], v[144:147], v[198:201], v[50:53]
	v_mfma_f32_16x16x32_bf16 v[46:49], v[152:155], v[198:201], v[46:49]
	v_mfma_f32_16x16x32_bf16 v[34:37], v[144:147], v[206:209], v[34:37]
	v_mfma_f32_16x16x32_bf16 v[30:33], v[152:155], v[206:209], v[30:33]
	v_mfma_f32_16x16x32_bf16 v[18:21], v[144:147], v[214:217], v[18:21]
	v_mfma_f32_16x16x32_bf16 v[14:17], v[152:155], v[214:217], v[14:17]
	v_mfma_f32_16x16x32_bf16 v[66:69], v[148:151], v[184:187], v[66:69]
	v_mfma_f32_16x16x32_bf16 v[62:65], v[156:159], v[184:187], v[62:65]
	v_mfma_f32_16x16x32_bf16 v[50:53], v[148:151], v[202:205], v[50:53]
	v_mfma_f32_16x16x32_bf16 v[46:49], v[156:159], v[202:205], v[46:49]
	v_mfma_f32_16x16x32_bf16 v[34:37], v[148:151], v[210:213], v[34:37]
	v_mfma_f32_16x16x32_bf16 v[30:33], v[156:159], v[210:213], v[30:33]
	v_mfma_f32_16x16x32_bf16 v[18:21], v[148:151], v[236:239], v[18:21]
	v_mfma_f32_16x16x32_bf16 v[14:17], v[156:159], v[236:239], v[14:17]
	v_mfma_f32_16x16x32_bf16 v[58:61], v[160:163], v[180:183], v[58:61]
	v_mfma_f32_16x16x32_bf16 v[54:57], v[172:175], v[180:183], v[54:57]
	v_mfma_f32_16x16x32_bf16 v[42:45], v[160:163], v[198:201], v[42:45]
	v_mfma_f32_16x16x32_bf16 v[38:41], v[172:175], v[198:201], v[38:41]
	v_mfma_f32_16x16x32_bf16 v[26:29], v[160:163], v[206:209], v[26:29]
	v_mfma_f32_16x16x32_bf16 v[22:25], v[172:175], v[206:209], v[22:25]
	v_mfma_f32_16x16x32_bf16 v[10:13], v[160:163], v[214:217], v[10:13]
	v_mfma_f32_16x16x32_bf16 v[6:9], v[172:175], v[214:217], v[6:9]
	v_mfma_f32_16x16x32_bf16 v[58:61], v[164:167], v[184:187], v[58:61]
	v_mfma_f32_16x16x32_bf16 v[54:57], v[176:179], v[184:187], v[54:57]
	v_mfma_f32_16x16x32_bf16 v[42:45], v[164:167], v[202:205], v[42:45]
	v_mfma_f32_16x16x32_bf16 v[38:41], v[176:179], v[202:205], v[38:41]
	v_mfma_f32_16x16x32_bf16 v[26:29], v[164:167], v[210:213], v[26:29]
	v_mfma_f32_16x16x32_bf16 v[22:25], v[176:179], v[210:213], v[22:25]
	v_mfma_f32_16x16x32_bf16 v[10:13], v[164:167], v[236:239], v[10:13]
	v_mfma_f32_16x16x32_bf16 v[6:9], v[176:179], v[236:239], v[6:9]
	s_setprio 0
	s_barrier
	s_add_i32 s64, s64, 2
	s_add_u32 s62, s62, 0x100
	s_addc_u32 s63, s63, 0
	s_add_u32 s54, s54, 0x100
	s_addc_u32 s55, s55, 0
	s_cmp_gt_u32 s64, 29
	s_cbranch_scc0 .LBB0_80
	s_and_b64 vcc, exec, s[42:43]
	s_cbranch_vccz .LBB0_83
	s_barrier

.LBB0_110:
	s_add_u32 s54, s52, 0xfff80080
	s_addc_u32 s55, s53, -1
	s_add_i32 s64, 0, 0x10000
	s_cmp_eq_u32 s63, 28
	s_cselect_b32 s57, s4, s55
	s_cselect_b32 s56, s5, s54
	s_cselect_b32 s55, s37, s62
	s_cselect_b32 s54, s43, s61
	s_add_i32 s66, 0, 0x14000
	v_add_u32_e32 v156, s64, v163
	v_add_u32_e32 v160, s66, v163
	ds_read_b128 v[134:137], v156
	ds_read_b128 v[138:141], v156 offset:1024
	ds_read_b128 v[152:155], v156 offset:2048
	ds_read_b128 v[156:159], v156 offset:3072
	ds_read_b128 v[166:169], v160
	ds_read_b128 v[170:173], v160 offset:1024
	ds_read_b128 v[174:177], v160 offset:2048
	ds_read_b128 v[178:181], v160 offset:3072
	v_lshl_add_u64 v[160:161], s[52:53], 0, v[150:151]
	s_add_i32 m0, s21, 0xc000
	ds_read_b128 v[182:185], v165
	ds_read_b128 v[186:189], v165 offset:1024
	ds_read_b128 v[198:201], v165 offset:2048
	ds_read_b128 v[202:205], v165 offset:3072
	ds_read_b128 v[206:209], v165 offset:4096
	ds_read_b128 v[210:213], v165 offset:5120
	ds_read_b128 v[214:217], v165 offset:6144
	ds_read_b128 v[236:239], v165 offset:7168
	global_load_lds_dwordx4 v[160:161], off
	v_lshl_add_u64 v[160:161], s[52:53], 0, v[148:149]
	s_add_i32 m0, s21, 0xe000
	s_nop 0
	global_load_lds_dwordx4 v[160:161], off
	s_waitcnt vmcnt(8)
	s_waitcnt lgkmcnt(0)
	s_barrier
	s_setprio 1
	s_waitcnt lgkmcnt(0)
	v_mfma_f32_16x16x32_bf16 v[130:133], v[134:137], v[182:185], v[130:133]
	v_mfma_f32_16x16x32_bf16 v[126:129], v[152:155], v[182:185], v[126:129]
	v_mfma_f32_16x16x32_bf16 v[114:117], v[134:137], v[198:201], v[114:117]
	v_mfma_f32_16x16x32_bf16 v[110:113], v[152:155], v[198:201], v[110:113]
	v_mfma_f32_16x16x32_bf16 v[98:101], v[134:137], v[206:209], v[98:101]
	v_mfma_f32_16x16x32_bf16 v[94:97], v[152:155], v[206:209], v[94:97]
	v_mfma_f32_16x16x32_bf16 v[82:85], v[134:137], v[214:217], v[82:85]
	v_mfma_f32_16x16x32_bf16 v[78:81], v[152:155], v[214:217], v[78:81]
	v_mfma_f32_16x16x32_bf16 v[130:133], v[138:141], v[186:189], v[130:133]
	v_mfma_f32_16x16x32_bf16 v[126:129], v[156:159], v[186:189], v[126:129]
	v_mfma_f32_16x16x32_bf16 v[114:117], v[138:141], v[202:205], v[114:117]
	v_mfma_f32_16x16x32_bf16 v[110:113], v[156:159], v[202:205], v[110:113]
	v_mfma_f32_16x16x32_bf16 v[98:101], v[138:141], v[210:213], v[98:101]
	v_mfma_f32_16x16x32_bf16 v[94:97], v[156:159], v[210:213], v[94:97]
	v_mfma_f32_16x16x32_bf16 v[82:85], v[138:141], v[236:239], v[82:85]
	v_mfma_f32_16x16x32_bf16 v[78:81], v[156:159], v[236:239], v[78:81]
	v_mfma_f32_16x16x32_bf16 v[122:125], v[166:169], v[182:185], v[122:125]
	v_mfma_f32_16x16x32_bf16 v[118:121], v[174:177], v[182:185], v[118:121]
	v_mfma_f32_16x16x32_bf16 v[106:109], v[166:169], v[198:201], v[106:109]
	v_mfma_f32_16x16x32_bf16 v[102:105], v[174:177], v[198:201], v[102:105]
	v_mfma_f32_16x16x32_bf16 v[90:93], v[166:169], v[206:209], v[90:93]
	v_mfma_f32_16x16x32_bf16 v[86:89], v[174:177], v[206:209], v[86:89]
	v_mfma_f32_16x16x32_bf16 v[74:77], v[166:169], v[214:217], v[74:77]
	v_mfma_f32_16x16x32_bf16 v[70:73], v[174:177], v[214:217], v[70:73]
	v_mfma_f32_16x16x32_bf16 v[122:125], v[170:173], v[186:189], v[122:125]
	v_mfma_f32_16x16x32_bf16 v[118:121], v[178:181], v[186:189], v[118:121]
	v_mfma_f32_16x16x32_bf16 v[106:109], v[170:173], v[202:205], v[106:109]
	v_mfma_f32_16x16x32_bf16 v[102:105], v[178:181], v[202:205], v[102:105]
	v_mfma_f32_16x16x32_bf16 v[90:93], v[170:173], v[210:213], v[90:93]
	v_mfma_f32_16x16x32_bf16 v[86:89], v[178:181], v[210:213], v[86:89]
	v_mfma_f32_16x16x32_bf16 v[74:77], v[170:173], v[236:239], v[74:77]
	v_mfma_f32_16x16x32_bf16 v[70:73], v[178:181], v[236:239], v[70:73]
	s_setprio 0
	s_barrier
	s_add_i32 s64, s64, s15
	v_lshl_add_u64 v[160:161], s[54:55], 0, v[190:191]
	s_mov_b32 m0, s64
	ds_read_b128 v[182:185], v165 offset:16384
	ds_read_b128 v[186:189], v165 offset:17408
	ds_read_b128 v[198:201], v165 offset:18432
	ds_read_b128 v[202:205], v165 offset:19456
	ds_read_b128 v[206:209], v165 offset:20480
	ds_read_b128 v[210:213], v165 offset:21504
	ds_read_b128 v[214:217], v165 offset:22528
	ds_read_b128 v[236:239], v165 offset:23552
	global_load_lds_dwordx4 v[160:161], off
	s_add_i32 m0, s64, 0x2000
	s_add_u32 s64, s54, 0x80000
	v_lshl_add_u64 v[218:219], s[54:55], 0, v[146:147]
	s_addc_u32 s65, s55, 0
	s_add_i32 s66, s66, s15
	global_load_lds_dwordx4 v[218:219], off
	v_lshl_add_u64 v[240:241], s[64:65], 0, v[190:191]
	s_mov_b32 m0, s66
	v_lshl_add_u64 v[242:243], s[56:57], 0, v[144:145]
	global_load_lds_dwordx4 v[240:241], off
	v_lshl_add_u64 v[240:241], s[64:65], 0, v[146:147]
	s_add_i32 m0, s66, 0x2000
	s_nop 0
	global_load_lds_dwordx4 v[240:241], off
	v_lshl_add_u64 v[240:241], s[56:57], 0, v[142:143]
	s_mov_b32 m0, s21
	s_nop 0
	global_load_lds_dwordx4 v[240:241], off
	s_mov_b32 m0, s23
	s_nop 0
	global_load_lds_dwordx4 v[242:243], off
	s_waitcnt vmcnt(8)
	s_waitcnt lgkmcnt(0)
	s_barrier
	s_setprio 1
	s_waitcnt lgkmcnt(0)
	v_mfma_f32_16x16x32_bf16 v[66:69], v[134:137], v[182:185], v[66:69]
	v_mfma_f32_16x16x32_bf16 v[62:65], v[152:155], v[182:185], v[62:65]
	v_mfma_f32_16x16x32_bf16 v[50:53], v[134:137], v[198:201], v[50:53]
	v_mfma_f32_16x16x32_bf16 v[46:49], v[152:155], v[198:201], v[46:49]
	v_mfma_f32_16x16x32_bf16 v[34:37], v[134:137], v[206:209], v[34:37]
	v_mfma_f32_16x16x32_bf16 v[30:33], v[152:155], v[206:209], v[30:33]
	v_mfma_f32_16x16x32_bf16 v[18:21], v[134:137], v[214:217], v[18:21]
	v_mfma_f32_16x16x32_bf16 v[14:17], v[152:155], v[214:217], v[14:17]
	v_mfma_f32_16x16x32_bf16 v[66:69], v[138:141], v[186:189], v[66:69]
	v_mfma_f32_16x16x32_bf16 v[62:65], v[156:159], v[186:189], v[62:65]
	v_mfma_f32_16x16x32_bf16 v[50:53], v[138:141], v[202:205], v[50:53]
	v_mfma_f32_16x16x32_bf16 v[46:49], v[156:159], v[202:205], v[46:49]
	v_mfma_f32_16x16x32_bf16 v[34:37], v[138:141], v[210:213], v[34:37]
	v_mfma_f32_16x16x32_bf16 v[30:33], v[156:159], v[210:213], v[30:33]
	v_mfma_f32_16x16x32_bf16 v[18:21], v[138:141], v[236:239], v[18:21]
	v_mfma_f32_16x16x32_bf16 v[14:17], v[156:159], v[236:239], v[14:17]
	v_mfma_f32_16x16x32_bf16 v[58:61], v[166:169], v[182:185], v[58:61]
	v_mfma_f32_16x16x32_bf16 v[54:57], v[174:177], v[182:185], v[54:57]
	v_mfma_f32_16x16x32_bf16 v[42:45], v[166:169], v[198:201], v[42:45]
	v_mfma_f32_16x16x32_bf16 v[38:41], v[174:177], v[198:201], v[38:41]
	v_mfma_f32_16x16x32_bf16 v[26:29], v[166:169], v[206:209], v[26:29]
	v_mfma_f32_16x16x32_bf16 v[22:25], v[174:177], v[206:209], v[22:25]
	v_mfma_f32_16x16x32_bf16 v[10:13], v[166:169], v[214:217], v[10:13]
	v_mfma_f32_16x16x32_bf16 v[6:9], v[174:177], v[214:217], v[6:9]
	v_mfma_f32_16x16x32_bf16 v[58:61], v[170:173], v[186:189], v[58:61]
	v_mfma_f32_16x16x32_bf16 v[54:57], v[178:181], v[186:189], v[54:57]
	v_mfma_f32_16x16x32_bf16 v[42:45], v[170:173], v[202:205], v[42:45]
	v_mfma_f32_16x16x32_bf16 v[38:41], v[178:181], v[202:205], v[38:41]
	v_mfma_f32_16x16x32_bf16 v[26:29], v[170:173], v[210:213], v[26:29]
	v_mfma_f32_16x16x32_bf16 v[22:25], v[178:181], v[210:213], v[22:25]
	v_mfma_f32_16x16x32_bf16 v[10:13], v[170:173], v[236:239], v[10:13]
	v_mfma_f32_16x16x32_bf16 v[6:9], v[178:181], v[236:239], v[6:9]
	s_setprio 0
	s_barrier
	s_add_i32 s64, 0, 0x18000
	s_add_i32 s65, 0, 0x1c000
	v_add_u32_e32 v156, s64, v163
	v_add_u32_e32 v178, s65, v163
	ds_read_b128 v[134:137], v156
	ds_read_b128 v[138:141], v156 offset:1024
	ds_read_b128 v[152:155], v156 offset:2048
	ds_read_b128 v[156:159], v156 offset:3072
	ds_read_b128 v[166:169], v178
	ds_read_b128 v[170:173], v178 offset:1024
	ds_read_b128 v[174:177], v178 offset:2048
	ds_read_b128 v[178:181], v178 offset:3072
	s_add_u32 s56, s56, 0x80000
	s_addc_u32 s57, s57, 0
	s_mov_b32 m0, s26
	v_lshl_add_u64 v[244:245], s[56:57], 0, v[142:143]
	ds_read_b128 v[182:185], v165 offset:32768
	ds_read_b128 v[186:189], v165 offset:33792
	ds_read_b128 v[198:201], v165 offset:34816
	ds_read_b128 v[202:205], v165 offset:35840
	ds_read_b128 v[206:209], v165 offset:36864
	ds_read_b128 v[210:213], v165 offset:37888
	ds_read_b128 v[214:217], v165 offset:38912
	ds_read_b128 v[236:239], v165 offset:39936
	global_load_lds_dwordx4 v[244:245], off
	v_lshl_add_u64 v[244:245], s[56:57], 0, v[144:145]
	s_mov_b32 m0, s29
	s_nop 0
	global_load_lds_dwordx4 v[244:245], off
	s_waitcnt vmcnt(8)
	s_waitcnt lgkmcnt(0)
	s_barrier
	s_setprio 1
	s_waitcnt lgkmcnt(0)
	v_mfma_f32_16x16x32_bf16 v[130:133], v[134:137], v[182:185], v[130:133]
	v_mfma_f32_16x16x32_bf16 v[126:129], v[152:155], v[182:185], v[126:129]
	v_mfma_f32_16x16x32_bf16 v[114:117], v[134:137], v[198:201], v[114:117]
	v_mfma_f32_16x16x32_bf16 v[110:113], v[152:155], v[198:201], v[110:113]
	v_mfma_f32_16x16x32_bf16 v[98:101], v[134:137], v[206:209], v[98:101]
	v_mfma_f32_16x16x32_bf16 v[94:97], v[152:155], v[206:209], v[94:97]
	v_mfma_f32_16x16x32_bf16 v[82:85], v[134:137], v[214:217], v[82:85]
	v_mfma_f32_16x16x32_bf16 v[78:81], v[152:155], v[214:217], v[78:81]
	v_mfma_f32_16x16x32_bf16 v[130:133], v[138:141], v[186:189], v[130:133]
	v_mfma_f32_16x16x32_bf16 v[126:129], v[156:159], v[186:189], v[126:129]
	v_mfma_f32_16x16x32_bf16 v[114:117], v[138:141], v[202:205], v[114:117]
	v_mfma_f32_16x16x32_bf16 v[110:113], v[156:159], v[202:205], v[110:113]
	v_mfma_f32_16x16x32_bf16 v[98:101], v[138:141], v[210:213], v[98:101]
	v_mfma_f32_16x16x32_bf16 v[94:97], v[156:159], v[210:213], v[94:97]
	v_mfma_f32_16x16x32_bf16 v[82:85], v[138:141], v[236:239], v[82:85]
	v_mfma_f32_16x16x32_bf16 v[78:81], v[156:159], v[236:239], v[78:81]
	v_mfma_f32_16x16x32_bf16 v[122:125], v[166:169], v[182:185], v[122:125]
	v_mfma_f32_16x16x32_bf16 v[118:121], v[174:177], v[182:185], v[118:121]
	v_mfma_f32_16x16x32_bf16 v[106:109], v[166:169], v[198:201], v[106:109]
	v_mfma_f32_16x16x32_bf16 v[102:105], v[174:177], v[198:201], v[102:105]
	v_mfma_f32_16x16x32_bf16 v[90:93], v[166:169], v[206:209], v[90:93]
	v_mfma_f32_16x16x32_bf16 v[86:89], v[174:177], v[206:209], v[86:89]
	v_mfma_f32_16x16x32_bf16 v[74:77], v[166:169], v[214:217], v[74:77]
	v_mfma_f32_16x16x32_bf16 v[70:73], v[174:177], v[214:217], v[70:73]
	v_mfma_f32_16x16x32_bf16 v[122:125], v[170:173], v[186:189], v[122:125]
	v_mfma_f32_16x16x32_bf16 v[118:121], v[178:181], v[186:189], v[118:121]
	v_mfma_f32_16x16x32_bf16 v[106:109], v[170:173], v[202:205], v[106:109]
	v_mfma_f32_16x16x32_bf16 v[102:105], v[178:181], v[202:205], v[102:105]
	v_mfma_f32_16x16x32_bf16 v[90:93], v[170:173], v[210:213], v[90:93]
	v_mfma_f32_16x16x32_bf16 v[86:89], v[178:181], v[210:213], v[86:89]
	v_mfma_f32_16x16x32_bf16 v[74:77], v[170:173], v[236:239], v[74:77]
	v_mfma_f32_16x16x32_bf16 v[70:73], v[178:181], v[236:239], v[70:73]
	s_setprio 0
	s_barrier
	s_add_i32 s56, s64, s15
	v_lshl_add_u64 v[160:161], v[160:161], 0, s[30:31]
	s_mov_b32 m0, s56
	ds_read_b128 v[182:185], v165 offset:49152
	ds_read_b128 v[186:189], v165 offset:50176
	ds_read_b128 v[198:201], v165 offset:51200
	ds_read_b128 v[202:205], v165 offset:52224
	ds_read_b128 v[206:209], v165 offset:53248
	ds_read_b128 v[210:213], v165 offset:54272
	ds_read_b128 v[214:217], v165 offset:55296
	ds_read_b128 v[236:239], v165 offset:56320
	global_load_lds_dwordx4 v[160:161], off
	s_add_i32 m0, s56, 0x2000
	s_add_u32 s54, s54, 0x80080
	v_lshl_add_u64 v[160:161], v[218:219], 0, s[30:31]
	s_addc_u32 s55, s55, 0
	s_add_i32 s56, s65, s15
	global_load_lds_dwordx4 v[160:161], off
	v_lshl_add_u64 v[160:161], s[54:55], 0, v[190:191]
	s_mov_b32 m0, s56
	s_nop 0
	global_load_lds_dwordx4 v[160:161], off
	v_lshl_add_u64 v[160:161], s[54:55], 0, v[146:147]
	s_add_i32 m0, s56, 0x2000
	s_nop 0
	global_load_lds_dwordx4 v[160:161], off
	v_lshl_add_u64 v[160:161], v[240:241], 0, s[30:31]
	s_mov_b32 m0, s51
	s_nop 0
	global_load_lds_dwordx4 v[160:161], off
	v_lshl_add_u64 v[160:161], v[242:243], 0, s[30:31]
	s_mov_b32 m0, s58
	s_nop 0
	global_load_lds_dwordx4 v[160:161], off
	s_waitcnt vmcnt(8)
	s_waitcnt lgkmcnt(0)
	s_barrier
	s_setprio 1
	s_waitcnt lgkmcnt(0)
	v_mfma_f32_16x16x32_bf16 v[66:69], v[134:137], v[182:185], v[66:69]
	v_mfma_f32_16x16x32_bf16 v[62:65], v[152:155], v[182:185], v[62:65]
	v_mfma_f32_16x16x32_bf16 v[50:53], v[134:137], v[198:201], v[50:53]
	v_mfma_f32_16x16x32_bf16 v[46:49], v[152:155], v[198:201], v[46:49]
	v_mfma_f32_16x16x32_bf16 v[34:37], v[134:137], v[206:209], v[34:37]
	v_mfma_f32_16x16x32_bf16 v[30:33], v[152:155], v[206:209], v[30:33]
	v_mfma_f32_16x16x32_bf16 v[18:21], v[134:137], v[214:217], v[18:21]
	v_mfma_f32_16x16x32_bf16 v[14:17], v[152:155], v[214:217], v[14:17]
	v_mfma_f32_16x16x32_bf16 v[66:69], v[138:141], v[186:189], v[66:69]
	v_mfma_f32_16x16x32_bf16 v[62:65], v[156:159], v[186:189], v[62:65]
	v_mfma_f32_16x16x32_bf16 v[50:53], v[138:141], v[202:205], v[50:53]
	v_mfma_f32_16x16x32_bf16 v[46:49], v[156:159], v[202:205], v[46:49]
	v_mfma_f32_16x16x32_bf16 v[34:37], v[138:141], v[210:213], v[34:37]
	v_mfma_f32_16x16x32_bf16 v[30:33], v[156:159], v[210:213], v[30:33]
	v_mfma_f32_16x16x32_bf16 v[18:21], v[138:141], v[236:239], v[18:21]
	v_mfma_f32_16x16x32_bf16 v[14:17], v[156:159], v[236:239], v[14:17]
	v_mfma_f32_16x16x32_bf16 v[58:61], v[166:169], v[182:185], v[58:61]
	v_mfma_f32_16x16x32_bf16 v[54:57], v[174:177], v[182:185], v[54:57]
	v_mfma_f32_16x16x32_bf16 v[42:45], v[166:169], v[198:201], v[42:45]
	v_mfma_f32_16x16x32_bf16 v[38:41], v[174:177], v[198:201], v[38:41]
	v_mfma_f32_16x16x32_bf16 v[26:29], v[166:169], v[206:209], v[26:29]
	v_mfma_f32_16x16x32_bf16 v[22:25], v[174:177], v[206:209], v[22:25]
	v_mfma_f32_16x16x32_bf16 v[10:13], v[166:169], v[214:217], v[10:13]
	v_mfma_f32_16x16x32_bf16 v[6:9], v[174:177], v[214:217], v[6:9]
	v_mfma_f32_16x16x32_bf16 v[58:61], v[170:173], v[186:189], v[58:61]
	v_mfma_f32_16x16x32_bf16 v[54:57], v[178:181], v[186:189], v[54:57]
	v_mfma_f32_16x16x32_bf16 v[42:45], v[170:173], v[202:205], v[42:45]
	v_mfma_f32_16x16x32_bf16 v[38:41], v[178:181], v[202:205], v[38:41]
	v_mfma_f32_16x16x32_bf16 v[26:29], v[170:173], v[210:213], v[26:29]
	v_mfma_f32_16x16x32_bf16 v[22:25], v[178:181], v[210:213], v[22:25]
	v_mfma_f32_16x16x32_bf16 v[10:13], v[170:173], v[236:239], v[10:13]
	v_mfma_f32_16x16x32_bf16 v[6:9], v[178:181], v[236:239], v[6:9]
	s_setprio 0
	s_barrier
	s_add_i32 s63, s63, 2
	s_add_u32 s61, s61, 0x100
	s_addc_u32 s62, s62, 0
	s_add_u32 s52, s52, 0x100
	s_addc_u32 s53, s53, 0
	s_cmp_gt_u32 s63, 29
	s_cbranch_scc0 .LBB0_110
	v_lshl_or_b32 v152, s50, 8, v164
	v_lshl_add_u32 v154, s48, 8, v162
	v_ashrrev_i32_e32 v153, 31, v152
	v_readlane_b32 s4, v255, 14
	v_ashrrev_i32_e32 v155, 31, v154
	v_lshlrev_b64 v[176:177], 1, v[152:153]
	v_readlane_b32 s5, v255, 15
	v_lshlrev_b64 v[158:159], 12, v[154:155]
	v_or_b32_e32 v160, 16, v154
	v_lshl_add_u64 v[156:157], s[4:5], 0, v[176:177]
	v_lshl_add_u64 v[134:135], v[156:157], 0, v[158:159]
	global_load_dwordx4 v[168:171], v[134:135], off
	global_load_dwordx4 v[172:175], v[134:135], off offset:256
	v_ashrrev_i32_e32 v161, 31, v160
	v_lshlrev_b64 v[134:135], 12, v[160:161]
	v_lshl_add_u64 v[134:135], v[156:157], 0, v[134:135]
	global_load_dwordx4 v[138:141], v[134:135], off
	s_nop 0
	global_load_dwordx4 v[134:137], v[134:135], off offset:256
	v_and_b32_e32 v167, 64, v221
	v_xor_b32_e32 v166, 16, v221
	v_add_u32_e32 v167, 64, v167
	v_xor_b32_e32 v178, 32, v221
	v_cmp_lt_i32_e32 vcc, v166, v167
	s_waitcnt vmcnt(0)
	v_lshlrev_b32_e32 v180, 16, v170
	v_cndmask_b32_e32 v166, v221, v166, vcc
	v_cmp_lt_i32_e32 vcc, v178, v167
	v_and_b32_e32 v181, 0xffff0000, v170
	v_lshlrev_b32_e32 v170, 16, v171
	v_cndmask_b32_e32 v167, v221, v178, vcc
	v_lshl_add_u64 v[178:179], s[4:5], 0, v[158:159]
	v_lshl_add_u64 v[176:177], v[178:179], 0, v[176:177]
	v_lshlrev_b32_e32 v178, 16, v168
	v_and_b32_e32 v179, 0xffff0000, v168
	v_lshlrev_b32_e32 v168, 16, v169
	v_and_b32_e32 v169, 0xffff0000, v169
	v_and_b32_e32 v171, 0xffff0000, v171
	v_lshlrev_b32_e32 v182, 16, v172
	v_and_b32_e32 v183, 0xffff0000, v172
	v_lshlrev_b32_e32 v172, 16, v173
	v_and_b32_e32 v173, 0xffff0000, v173
	v_lshlrev_b32_e32 v184, 16, v174
	v_and_b32_e32 v185, 0xffff0000, v174
	v_lshlrev_b32_e32 v174, 16, v175
	v_and_b32_e32 v175, 0xffff0000, v175
	v_pk_add_f32 v[132:133], v[132:133], v[168:169]
	v_pk_add_f32 v[130:131], v[130:131], v[178:179]
	v_pk_add_f32 v[128:129], v[128:129], v[170:171]
	v_pk_add_f32 v[126:127], v[126:127], v[180:181]
	v_pk_add_f32 v[168:169], v[124:125], v[172:173]
	v_pk_add_f32 v[122:123], v[122:123], v[182:183]
	v_pk_add_f32 v[170:171], v[120:121], v[174:175]
	v_pk_add_f32 v[172:173], v[118:119], v[184:185]
	v_mul_f32_e32 v121, v131, v131
	v_mul_f32_e32 v124, v133, v133
	v_mul_f32_e32 v125, v127, v127
	v_mul_f32_e32 v174, v129, v129
	v_cvt_pk_bf16_f32 v118, v130, v131
	v_cvt_pk_bf16_f32 v119, v132, v133
	v_cvt_pk_bf16_f32 v120, v126, v127
	v_mul_f32_e32 v127, v123, v123
	v_mul_f32_e32 v131, v169, v169
	v_mul_f32_e32 v133, v173, v173
	v_mul_f32_e32 v175, v171, v171
	v_fmac_f32_e32 v121, v130, v130
	v_fmac_f32_e32 v124, v132, v132
	v_fmac_f32_e32 v125, v126, v126
	v_fmac_f32_e32 v174, v128, v128
	v_fmac_f32_e32 v127, v122, v122
	v_fmac_f32_e32 v131, v168, v168
	v_fmac_f32_e32 v133, v172, v172
	v_fmac_f32_e32 v175, v170, v170
	v_add_f32_e32 v121, v121, v124
	v_add_f32_e32 v124, v125, v174
	v_add_f32_e32 v125, v127, v131
	v_add_f32_e32 v126, v133, v175
	v_add_f32_e32 v121, v121, v124
	v_add_f32_e32 v124, v125, v126
	v_lshlrev_b32_e32 v166, 2, v166
	v_add_f32_e32 v126, v121, v124
	ds_bpermute_b32 v127, v166, v126
	v_cvt_pk_bf16_f32 v121, v128, v129
	global_store_dwordx4 v[176:177], v[118:121], off
	v_cvt_pk_bf16_f32 v124, v122, v123
	v_cvt_pk_bf16_f32 v125, v168, v169
	s_waitcnt lgkmcnt(0)
	s_nop 0
	v_add_f32_e32 v121, v126, v127
	v_lshlrev_b32_e32 v120, 2, v167
	ds_bpermute_b32 v122, v120, v121
	v_lshl_add_u64 v[118:119], v[154:155], 3, s[18:19]
	v_cvt_pk_bf16_f32 v126, v172, v173
	v_cvt_pk_bf16_f32 v127, v170, v171
	global_store_dwordx4 v[176:177], v[124:127], off offset:256
	s_and_saveexec_b64 s[4:5], s[38:39]
	s_cbranch_execz .LBB0_113
	s_waitcnt lgkmcnt(0)
	v_add_f32_e32 v121, v121, v122
	v_mul_f32_e32 v121, 0x4b800000, v121
	v_trunc_f32_e32 v121, v121
	v_mul_f32_e32 v122, 0x2f800000, v121
	v_floor_f32_e32 v123, v122
	v_fmac_f32_e32 v121, 0xcf800000, v123
	v_cvt_u32_f32_e32 v122, v121
	v_cvt_u32_f32_e32 v123, v123
	global_atomic_add_x2 v[118:119], v[122:123], off

.LBB0_150:
	s_add_u32 s54, s52, 0xfff80080
	s_addc_u32 s55, s53, -1
	s_add_i32 s64, 0, 0x10000
	s_cmp_eq_u32 s63, 28
	s_cselect_b32 s57, s4, s55
	s_cselect_b32 s56, s5, s54
	s_cselect_b32 s55, s37, s62
	s_cselect_b32 s54, s43, s61
	s_add_i32 s66, 0, 0x14000
	v_add_u32_e32 v146, s64, v169
	v_add_u32_e32 v176, s66, v169
	ds_read_b128 v[134:137], v146
	ds_read_b128 v[138:141], v146 offset:1024
	ds_read_b128 v[142:145], v146 offset:2048
	ds_read_b128 v[146:149], v146 offset:3072
	ds_read_b128 v[160:163], v176
	ds_read_b128 v[164:167], v176 offset:1024
	ds_read_b128 v[172:175], v176 offset:2048
	ds_read_b128 v[176:179], v176 offset:3072
	v_lshl_add_u64 v[188:189], s[52:53], 0, v[158:159]
	s_add_i32 m0, s21, 0xc000
	ds_read_b128 v[180:183], v171
	ds_read_b128 v[184:187], v171 offset:1024
	ds_read_b128 v[198:201], v171 offset:2048
	ds_read_b128 v[202:205], v171 offset:3072
	ds_read_b128 v[206:209], v171 offset:4096
	ds_read_b128 v[210:213], v171 offset:5120
	ds_read_b128 v[214:217], v171 offset:6144
	ds_read_b128 v[236:239], v171 offset:7168
	global_load_lds_dwordx4 v[188:189], off
	v_lshl_add_u64 v[188:189], s[52:53], 0, v[156:157]
	s_add_i32 m0, s21, 0xe000
	s_nop 0
	global_load_lds_dwordx4 v[188:189], off
	s_waitcnt vmcnt(8)
	s_waitcnt lgkmcnt(0)
	s_barrier
	s_setprio 1
	s_waitcnt lgkmcnt(0)
	v_mfma_f32_16x16x32_bf16 v[130:133], v[134:137], v[180:183], v[130:133]
	v_mfma_f32_16x16x32_bf16 v[126:129], v[142:145], v[180:183], v[126:129]
	v_mfma_f32_16x16x32_bf16 v[114:117], v[134:137], v[198:201], v[114:117]
	v_mfma_f32_16x16x32_bf16 v[110:113], v[142:145], v[198:201], v[110:113]
	v_mfma_f32_16x16x32_bf16 v[98:101], v[134:137], v[206:209], v[98:101]
	v_mfma_f32_16x16x32_bf16 v[94:97], v[142:145], v[206:209], v[94:97]
	v_mfma_f32_16x16x32_bf16 v[82:85], v[134:137], v[214:217], v[82:85]
	v_mfma_f32_16x16x32_bf16 v[78:81], v[142:145], v[214:217], v[78:81]
	v_mfma_f32_16x16x32_bf16 v[130:133], v[138:141], v[184:187], v[130:133]
	v_mfma_f32_16x16x32_bf16 v[126:129], v[146:149], v[184:187], v[126:129]
	v_mfma_f32_16x16x32_bf16 v[114:117], v[138:141], v[202:205], v[114:117]
	v_mfma_f32_16x16x32_bf16 v[110:113], v[146:149], v[202:205], v[110:113]
	v_mfma_f32_16x16x32_bf16 v[98:101], v[138:141], v[210:213], v[98:101]
	v_mfma_f32_16x16x32_bf16 v[94:97], v[146:149], v[210:213], v[94:97]
	v_mfma_f32_16x16x32_bf16 v[82:85], v[138:141], v[236:239], v[82:85]
	v_mfma_f32_16x16x32_bf16 v[78:81], v[146:149], v[236:239], v[78:81]
	v_mfma_f32_16x16x32_bf16 v[122:125], v[160:163], v[180:183], v[122:125]
	v_mfma_f32_16x16x32_bf16 v[118:121], v[172:175], v[180:183], v[118:121]
	v_mfma_f32_16x16x32_bf16 v[106:109], v[160:163], v[198:201], v[106:109]
	v_mfma_f32_16x16x32_bf16 v[102:105], v[172:175], v[198:201], v[102:105]
	v_mfma_f32_16x16x32_bf16 v[90:93], v[160:163], v[206:209], v[90:93]
	v_mfma_f32_16x16x32_bf16 v[86:89], v[172:175], v[206:209], v[86:89]
	v_mfma_f32_16x16x32_bf16 v[74:77], v[160:163], v[214:217], v[74:77]
	v_mfma_f32_16x16x32_bf16 v[70:73], v[172:175], v[214:217], v[70:73]
	v_mfma_f32_16x16x32_bf16 v[122:125], v[164:167], v[184:187], v[122:125]
	v_mfma_f32_16x16x32_bf16 v[118:121], v[176:179], v[184:187], v[118:121]
	v_mfma_f32_16x16x32_bf16 v[106:109], v[164:167], v[202:205], v[106:109]
	v_mfma_f32_16x16x32_bf16 v[102:105], v[176:179], v[202:205], v[102:105]
	v_mfma_f32_16x16x32_bf16 v[90:93], v[164:167], v[210:213], v[90:93]
	v_mfma_f32_16x16x32_bf16 v[86:89], v[176:179], v[210:213], v[86:89]
	v_mfma_f32_16x16x32_bf16 v[74:77], v[164:167], v[236:239], v[74:77]
	v_mfma_f32_16x16x32_bf16 v[70:73], v[176:179], v[236:239], v[70:73]
	s_setprio 0
	s_barrier
	s_add_i32 s64, s64, s15
	v_lshl_add_u64 v[188:189], s[54:55], 0, v[190:191]
	s_mov_b32 m0, s64
	ds_read_b128 v[180:183], v171 offset:16384
	ds_read_b128 v[184:187], v171 offset:17408
	ds_read_b128 v[198:201], v171 offset:18432
	ds_read_b128 v[202:205], v171 offset:19456
	ds_read_b128 v[206:209], v171 offset:20480
	ds_read_b128 v[210:213], v171 offset:21504
	ds_read_b128 v[214:217], v171 offset:22528
	ds_read_b128 v[236:239], v171 offset:23552
	global_load_lds_dwordx4 v[188:189], off
	s_add_i32 m0, s64, 0x2000
	s_add_u32 s64, s54, 0x80000
	v_lshl_add_u64 v[218:219], s[54:55], 0, v[154:155]
	s_addc_u32 s65, s55, 0
	s_add_i32 s66, s66, s15
	global_load_lds_dwordx4 v[218:219], off
	v_lshl_add_u64 v[240:241], s[64:65], 0, v[190:191]
	s_mov_b32 m0, s66
	v_lshl_add_u64 v[242:243], s[56:57], 0, v[152:153]
	global_load_lds_dwordx4 v[240:241], off
	v_lshl_add_u64 v[240:241], s[64:65], 0, v[154:155]
	s_add_i32 m0, s66, 0x2000
	s_nop 0
	global_load_lds_dwordx4 v[240:241], off
	v_lshl_add_u64 v[240:241], s[56:57], 0, v[150:151]
	s_mov_b32 m0, s21
	s_nop 0
	global_load_lds_dwordx4 v[240:241], off
	s_mov_b32 m0, s23
	s_nop 0
	global_load_lds_dwordx4 v[242:243], off
	s_waitcnt vmcnt(8)
	s_waitcnt lgkmcnt(0)
	s_barrier
	s_setprio 1
	s_waitcnt lgkmcnt(0)
	v_mfma_f32_16x16x32_bf16 v[66:69], v[134:137], v[180:183], v[66:69]
	v_mfma_f32_16x16x32_bf16 v[62:65], v[142:145], v[180:183], v[62:65]
	v_mfma_f32_16x16x32_bf16 v[50:53], v[134:137], v[198:201], v[50:53]
	v_mfma_f32_16x16x32_bf16 v[46:49], v[142:145], v[198:201], v[46:49]
	v_mfma_f32_16x16x32_bf16 v[34:37], v[134:137], v[206:209], v[34:37]
	v_mfma_f32_16x16x32_bf16 v[30:33], v[142:145], v[206:209], v[30:33]
	v_mfma_f32_16x16x32_bf16 v[18:21], v[134:137], v[214:217], v[18:21]
	v_mfma_f32_16x16x32_bf16 v[14:17], v[142:145], v[214:217], v[14:17]
	v_mfma_f32_16x16x32_bf16 v[66:69], v[138:141], v[184:187], v[66:69]
	v_mfma_f32_16x16x32_bf16 v[62:65], v[146:149], v[184:187], v[62:65]
	v_mfma_f32_16x16x32_bf16 v[50:53], v[138:141], v[202:205], v[50:53]
	v_mfma_f32_16x16x32_bf16 v[46:49], v[146:149], v[202:205], v[46:49]
	v_mfma_f32_16x16x32_bf16 v[34:37], v[138:141], v[210:213], v[34:37]
	v_mfma_f32_16x16x32_bf16 v[30:33], v[146:149], v[210:213], v[30:33]
	v_mfma_f32_16x16x32_bf16 v[18:21], v[138:141], v[236:239], v[18:21]
	v_mfma_f32_16x16x32_bf16 v[14:17], v[146:149], v[236:239], v[14:17]
	v_mfma_f32_16x16x32_bf16 v[58:61], v[160:163], v[180:183], v[58:61]
	v_mfma_f32_16x16x32_bf16 v[54:57], v[172:175], v[180:183], v[54:57]
	v_mfma_f32_16x16x32_bf16 v[42:45], v[160:163], v[198:201], v[42:45]
	v_mfma_f32_16x16x32_bf16 v[38:41], v[172:175], v[198:201], v[38:41]
	v_mfma_f32_16x16x32_bf16 v[26:29], v[160:163], v[206:209], v[26:29]
	v_mfma_f32_16x16x32_bf16 v[22:25], v[172:175], v[206:209], v[22:25]
	v_mfma_f32_16x16x32_bf16 v[10:13], v[160:163], v[214:217], v[10:13]
	v_mfma_f32_16x16x32_bf16 v[6:9], v[172:175], v[214:217], v[6:9]
	v_mfma_f32_16x16x32_bf16 v[58:61], v[164:167], v[184:187], v[58:61]
	v_mfma_f32_16x16x32_bf16 v[54:57], v[176:179], v[184:187], v[54:57]
	v_mfma_f32_16x16x32_bf16 v[42:45], v[164:167], v[202:205], v[42:45]
	v_mfma_f32_16x16x32_bf16 v[38:41], v[176:179], v[202:205], v[38:41]
	v_mfma_f32_16x16x32_bf16 v[26:29], v[164:167], v[210:213], v[26:29]
	v_mfma_f32_16x16x32_bf16 v[22:25], v[176:179], v[210:213], v[22:25]
	v_mfma_f32_16x16x32_bf16 v[10:13], v[164:167], v[236:239], v[10:13]
	v_mfma_f32_16x16x32_bf16 v[6:9], v[176:179], v[236:239], v[6:9]
	s_setprio 0
	s_barrier
	s_add_i32 s64, 0, 0x18000
	s_add_i32 s65, 0, 0x1c000
	v_add_u32_e32 v146, s64, v169
	v_add_u32_e32 v176, s65, v169
	ds_read_b128 v[134:137], v146
	ds_read_b128 v[138:141], v146 offset:1024
	ds_read_b128 v[142:145], v146 offset:2048
	ds_read_b128 v[146:149], v146 offset:3072
	ds_read_b128 v[160:163], v176
	ds_read_b128 v[164:167], v176 offset:1024
	ds_read_b128 v[172:175], v176 offset:2048
	ds_read_b128 v[176:179], v176 offset:3072
	s_add_u32 s56, s56, 0x80000
	s_addc_u32 s57, s57, 0
	s_mov_b32 m0, s26
	v_lshl_add_u64 v[244:245], s[56:57], 0, v[150:151]
	ds_read_b128 v[180:183], v171 offset:32768
	ds_read_b128 v[184:187], v171 offset:33792
	ds_read_b128 v[198:201], v171 offset:34816
	ds_read_b128 v[202:205], v171 offset:35840
	ds_read_b128 v[206:209], v171 offset:36864
	ds_read_b128 v[210:213], v171 offset:37888
	ds_read_b128 v[214:217], v171 offset:38912
	ds_read_b128 v[236:239], v171 offset:39936
	global_load_lds_dwordx4 v[244:245], off
	v_lshl_add_u64 v[244:245], s[56:57], 0, v[152:153]
	s_mov_b32 m0, s29
	s_nop 0
	global_load_lds_dwordx4 v[244:245], off
	s_waitcnt vmcnt(8)
	s_waitcnt lgkmcnt(0)
	s_barrier
	s_setprio 1
	s_waitcnt lgkmcnt(0)
	v_mfma_f32_16x16x32_bf16 v[130:133], v[134:137], v[180:183], v[130:133]
	v_mfma_f32_16x16x32_bf16 v[126:129], v[142:145], v[180:183], v[126:129]
	v_mfma_f32_16x16x32_bf16 v[114:117], v[134:137], v[198:201], v[114:117]
	v_mfma_f32_16x16x32_bf16 v[110:113], v[142:145], v[198:201], v[110:113]
	v_mfma_f32_16x16x32_bf16 v[98:101], v[134:137], v[206:209], v[98:101]
	v_mfma_f32_16x16x32_bf16 v[94:97], v[142:145], v[206:209], v[94:97]
	v_mfma_f32_16x16x32_bf16 v[82:85], v[134:137], v[214:217], v[82:85]
	v_mfma_f32_16x16x32_bf16 v[78:81], v[142:145], v[214:217], v[78:81]
	v_mfma_f32_16x16x32_bf16 v[130:133], v[138:141], v[184:187], v[130:133]
	v_mfma_f32_16x16x32_bf16 v[126:129], v[146:149], v[184:187], v[126:129]
	v_mfma_f32_16x16x32_bf16 v[114:117], v[138:141], v[202:205], v[114:117]
	v_mfma_f32_16x16x32_bf16 v[110:113], v[146:149], v[202:205], v[110:113]
	v_mfma_f32_16x16x32_bf16 v[98:101], v[138:141], v[210:213], v[98:101]
	v_mfma_f32_16x16x32_bf16 v[94:97], v[146:149], v[210:213], v[94:97]
	v_mfma_f32_16x16x32_bf16 v[82:85], v[138:141], v[236:239], v[82:85]
	v_mfma_f32_16x16x32_bf16 v[78:81], v[146:149], v[236:239], v[78:81]
	v_mfma_f32_16x16x32_bf16 v[122:125], v[160:163], v[180:183], v[122:125]
	v_mfma_f32_16x16x32_bf16 v[118:121], v[172:175], v[180:183], v[118:121]
	v_mfma_f32_16x16x32_bf16 v[106:109], v[160:163], v[198:201], v[106:109]
	v_mfma_f32_16x16x32_bf16 v[102:105], v[172:175], v[198:201], v[102:105]
	v_mfma_f32_16x16x32_bf16 v[90:93], v[160:163], v[206:209], v[90:93]
	v_mfma_f32_16x16x32_bf16 v[86:89], v[172:175], v[206:209], v[86:89]
	v_mfma_f32_16x16x32_bf16 v[74:77], v[160:163], v[214:217], v[74:77]
	v_mfma_f32_16x16x32_bf16 v[70:73], v[172:175], v[214:217], v[70:73]
	v_mfma_f32_16x16x32_bf16 v[122:125], v[164:167], v[184:187], v[122:125]
	v_mfma_f32_16x16x32_bf16 v[118:121], v[176:179], v[184:187], v[118:121]
	v_mfma_f32_16x16x32_bf16 v[106:109], v[164:167], v[202:205], v[106:109]
	v_mfma_f32_16x16x32_bf16 v[102:105], v[176:179], v[202:205], v[102:105]
	v_mfma_f32_16x16x32_bf16 v[90:93], v[164:167], v[210:213], v[90:93]
	v_mfma_f32_16x16x32_bf16 v[86:89], v[176:179], v[210:213], v[86:89]
	v_mfma_f32_16x16x32_bf16 v[74:77], v[164:167], v[236:239], v[74:77]
	v_mfma_f32_16x16x32_bf16 v[70:73], v[176:179], v[236:239], v[70:73]
	s_setprio 0
	s_barrier
	s_add_i32 s56, s64, s15
	v_lshl_add_u64 v[188:189], v[188:189], 0, s[30:31]
	s_mov_b32 m0, s56
	ds_read_b128 v[180:183], v171 offset:49152
	ds_read_b128 v[184:187], v171 offset:50176
	ds_read_b128 v[198:201], v171 offset:51200
	ds_read_b128 v[202:205], v171 offset:52224
	ds_read_b128 v[206:209], v171 offset:53248
	ds_read_b128 v[210:213], v171 offset:54272
	ds_read_b128 v[214:217], v171 offset:55296
	ds_read_b128 v[236:239], v171 offset:56320
	global_load_lds_dwordx4 v[188:189], off
	s_add_i32 m0, s56, 0x2000
	s_add_u32 s54, s54, 0x80080
	v_lshl_add_u64 v[188:189], v[218:219], 0, s[30:31]
	s_addc_u32 s55, s55, 0
	s_add_i32 s56, s65, s15
	global_load_lds_dwordx4 v[188:189], off
	v_lshl_add_u64 v[188:189], s[54:55], 0, v[190:191]
	s_mov_b32 m0, s56
	s_nop 0
	global_load_lds_dwordx4 v[188:189], off
	v_lshl_add_u64 v[188:189], s[54:55], 0, v[154:155]
	s_add_i32 m0, s56, 0x2000
	s_nop 0
	global_load_lds_dwordx4 v[188:189], off
	v_lshl_add_u64 v[188:189], v[240:241], 0, s[30:31]
	s_mov_b32 m0, s49
	s_nop 0
	global_load_lds_dwordx4 v[188:189], off
	v_lshl_add_u64 v[188:189], v[242:243], 0, s[30:31]
	s_mov_b32 m0, s51
	s_nop 0
	global_load_lds_dwordx4 v[188:189], off
	s_waitcnt vmcnt(8)
	s_waitcnt lgkmcnt(0)
	s_barrier
	s_setprio 1
	s_waitcnt lgkmcnt(0)
	v_mfma_f32_16x16x32_bf16 v[66:69], v[134:137], v[180:183], v[66:69]
	v_mfma_f32_16x16x32_bf16 v[62:65], v[142:145], v[180:183], v[62:65]
	v_mfma_f32_16x16x32_bf16 v[50:53], v[134:137], v[198:201], v[50:53]
	v_mfma_f32_16x16x32_bf16 v[46:49], v[142:145], v[198:201], v[46:49]
	v_mfma_f32_16x16x32_bf16 v[34:37], v[134:137], v[206:209], v[34:37]
	v_mfma_f32_16x16x32_bf16 v[30:33], v[142:145], v[206:209], v[30:33]
	v_mfma_f32_16x16x32_bf16 v[18:21], v[134:137], v[214:217], v[18:21]
	v_mfma_f32_16x16x32_bf16 v[14:17], v[142:145], v[214:217], v[14:17]
	v_mfma_f32_16x16x32_bf16 v[66:69], v[138:141], v[184:187], v[66:69]
	v_mfma_f32_16x16x32_bf16 v[62:65], v[146:149], v[184:187], v[62:65]
	v_mfma_f32_16x16x32_bf16 v[50:53], v[138:141], v[202:205], v[50:53]
	v_mfma_f32_16x16x32_bf16 v[46:49], v[146:149], v[202:205], v[46:49]
	v_mfma_f32_16x16x32_bf16 v[34:37], v[138:141], v[210:213], v[34:37]
	v_mfma_f32_16x16x32_bf16 v[30:33], v[146:149], v[210:213], v[30:33]
	v_mfma_f32_16x16x32_bf16 v[18:21], v[138:141], v[236:239], v[18:21]
	v_mfma_f32_16x16x32_bf16 v[14:17], v[146:149], v[236:239], v[14:17]
	v_mfma_f32_16x16x32_bf16 v[58:61], v[160:163], v[180:183], v[58:61]
	v_mfma_f32_16x16x32_bf16 v[54:57], v[172:175], v[180:183], v[54:57]
	v_mfma_f32_16x16x32_bf16 v[42:45], v[160:163], v[198:201], v[42:45]
	v_mfma_f32_16x16x32_bf16 v[38:41], v[172:175], v[198:201], v[38:41]
	v_mfma_f32_16x16x32_bf16 v[26:29], v[160:163], v[206:209], v[26:29]
	v_mfma_f32_16x16x32_bf16 v[22:25], v[172:175], v[206:209], v[22:25]
	v_mfma_f32_16x16x32_bf16 v[10:13], v[160:163], v[214:217], v[10:13]
	v_mfma_f32_16x16x32_bf16 v[6:9], v[172:175], v[214:217], v[6:9]
	v_mfma_f32_16x16x32_bf16 v[58:61], v[164:167], v[184:187], v[58:61]
	v_mfma_f32_16x16x32_bf16 v[54:57], v[176:179], v[184:187], v[54:57]
	v_mfma_f32_16x16x32_bf16 v[42:45], v[164:167], v[202:205], v[42:45]
	v_mfma_f32_16x16x32_bf16 v[38:41], v[176:179], v[202:205], v[38:41]
	v_mfma_f32_16x16x32_bf16 v[26:29], v[164:167], v[210:213], v[26:29]
	v_mfma_f32_16x16x32_bf16 v[22:25], v[176:179], v[210:213], v[22:25]
	v_mfma_f32_16x16x32_bf16 v[10:13], v[164:167], v[236:239], v[10:13]
	v_mfma_f32_16x16x32_bf16 v[6:9], v[176:179], v[236:239], v[6:9]
	s_setprio 0
	s_barrier
	s_add_i32 s63, s63, 2
	s_add_u32 s61, s61, 0x100
	s_addc_u32 s62, s62, 0
	s_add_u32 s52, s52, 0x100
	s_addc_u32 s53, s53, 0
	s_cmp_gt_u32 s63, 29
	s_cbranch_scc0 .LBB0_150
	s_load_dwordx2 s[4:5], s[70:71], 0x0
	v_lshl_add_u32 v162, s48, 8, v168
	v_lshl_or_b32 v160, s50, 8, v170
	v_ashrrev_i32_e32 v161, 31, v160
	v_ashrrev_i32_e32 v163, 31, v162
	s_waitcnt lgkmcnt(0)
	v_lshl_add_u64 v[164:165], v[160:161], 2, s[4:5]
	v_lshlrev_b64 v[134:135], 13, v[162:163]
	v_lshl_add_u64 v[134:135], v[164:165], 0, v[134:135]
	global_load_dwordx4 v[172:175], v[134:135], off offset:16
	global_load_dwordx4 v[176:179], v[134:135], off
	global_load_dwordx4 v[180:183], v[134:135], off offset:528
	global_load_dwordx4 v[184:187], v[134:135], off offset:512
	v_or_b32_e32 v166, 16, v162
	v_ashrrev_i32_e32 v167, 31, v166
	v_lshlrev_b64 v[134:135], 13, v[166:167]
	v_lshl_add_u64 v[138:139], v[164:165], 0, v[134:135]
	global_load_dwordx4 v[142:145], v[138:139], off offset:16
	global_load_dwordx4 v[146:149], v[138:139], off
	global_load_dwordx4 v[134:137], v[138:139], off offset:528
	s_nop 0
	global_load_dwordx4 v[138:141], v[138:139], off offset:512
	v_readlane_b32 s4, v255, 14
	v_lshlrev_b64 v[188:189], 12, v[162:163]
	v_readlane_b32 s5, v255, 15
	s_waitcnt vmcnt(0)
	v_pk_add_f32 v[174:175], v[128:129], v[174:175]
	v_pk_add_f32 v[132:133], v[132:133], v[178:179]
	v_pk_add_f32 v[130:131], v[130:131], v[176:177]
	v_pk_add_f32 v[128:129], v[126:127], v[172:173]
	v_mul_f32_e32 v126, v131, v131
	v_mul_f32_e32 v127, v133, v133
	v_fmac_f32_e32 v126, v130, v130
	v_fmac_f32_e32 v127, v132, v132
	v_add_f32_e32 v126, v126, v127
	v_mul_f32_e32 v127, v129, v129
	v_mul_f32_e32 v172, v175, v175
	v_fmac_f32_e32 v127, v128, v128
	v_fmac_f32_e32 v172, v174, v174
	v_lshl_add_u64 v[188:189], s[4:5], 0, v[188:189]
	v_add_f32_e32 v127, v127, v172
	v_lshl_add_u64 v[188:189], v[160:161], 1, v[188:189]
	v_add_f32_e32 v172, v126, v127
	v_cvt_pk_bf16_f32 v126, v130, v131
	v_cvt_pk_bf16_f32 v127, v132, v133
	v_pk_add_f32 v[124:125], v[124:125], v[186:187]
	v_pk_add_f32 v[122:123], v[122:123], v[184:185]
	v_cvt_pk_bf16_f32 v128, v128, v129
	v_cvt_pk_bf16_f32 v129, v174, v175
	global_store_dwordx4 v[188:189], v[126:129], off
	s_nop 1
	v_pk_add_f32 v[126:127], v[120:121], v[182:183]
	v_pk_add_f32 v[120:121], v[118:119], v[180:181]
	v_mul_f32_e32 v118, v123, v123
	v_mul_f32_e32 v119, v125, v125
	v_fmac_f32_e32 v118, v122, v122
	v_fmac_f32_e32 v119, v124, v124
	v_add_f32_e32 v118, v118, v119
	v_mul_f32_e32 v119, v121, v121
	v_mul_f32_e32 v128, v127, v127
	v_fmac_f32_e32 v119, v120, v120
	v_fmac_f32_e32 v128, v126, v126
	v_add_f32_e32 v119, v119, v128
	v_add_f32_e32 v118, v118, v119
	v_add_f32_e32 v128, v172, v118
	v_cvt_pk_bf16_f32 v118, v122, v123
	v_cvt_pk_bf16_f32 v119, v124, v125
	v_cvt_pk_bf16_f32 v120, v120, v121
	v_cvt_pk_bf16_f32 v121, v126, v127
	global_store_dwordx4 v[188:189], v[118:121], off offset:256
	s_nop 1
	v_and_b32_e32 v119, 64, v221
	v_xor_b32_e32 v118, 16, v221
	v_add_u32_e32 v119, 64, v119
	v_cmp_lt_i32_e32 vcc, v118, v119
	s_nop 1
	v_cndmask_b32_e32 v118, v221, v118, vcc
	v_lshlrev_b32_e32 v122, 2, v118
	ds_bpermute_b32 v118, v122, v128
	s_waitcnt lgkmcnt(0)
	v_add_f32_e32 v120, v128, v118
	v_xor_b32_e32 v118, 32, v221
	v_cmp_lt_i32_e32 vcc, v118, v119
	s_nop 1
	v_cndmask_b32_e32 v118, v221, v118, vcc
	v_lshlrev_b32_e32 v123, 2, v118
	ds_bpermute_b32 v121, v123, v120
	v_lshl_add_u64 v[118:119], v[162:163], 3, s[18:19]
	s_and_saveexec_b64 s[4:5], s[38:39]
	s_cbranch_execz .LBB0_153
	s_waitcnt lgkmcnt(0)
	v_add_f32_e32 v120, v120, v121
	v_mul_f32_e32 v120, 0x4b800000, v120
	v_trunc_f32_e32 v120, v120
	v_mul_f32_e32 v121, 0x2f800000, v120
	v_floor_f32_e32 v121, v121
	v_fmac_f32_e32 v120, 0xcf800000, v121
	v_cvt_u32_f32_e32 v120, v120
	v_cvt_u32_f32_e32 v121, v121
	global_atomic_add_x2 v[118:119], v[120:121], off

.LBB0_1054:
	s_add_u32 s58, s56, 0xfff80080
	s_addc_u32 s59, s57, -1
	s_add_i32 s65, 0, 0x10000
	s_cmp_eq_u32 s64, 28
	s_cselect_b32 s61, s4, s59
	s_cselect_b32 s60, s5, s58
	s_cselect_b32 s59, s45, s63
	s_cselect_b32 s58, s47, s62
	s_add_i32 s68, 0, 0x14000
	v_add_u32_e32 v156, s65, v163
	v_add_u32_e32 v160, s68, v163
	ds_read_b128 v[144:147], v156
	ds_read_b128 v[148:151], v156 offset:1024
	ds_read_b128 v[152:155], v156 offset:2048
	ds_read_b128 v[156:159], v156 offset:3072
	ds_read_b128 v[166:169], v160
	ds_read_b128 v[170:173], v160 offset:1024
	ds_read_b128 v[174:177], v160 offset:2048
	ds_read_b128 v[178:181], v160 offset:3072
	v_lshl_add_u64 v[160:161], s[56:57], 0, v[142:143]
	s_add_i32 m0, s2, 0xc000
	ds_read_b128 v[182:185], v165
	ds_read_b128 v[186:189], v165 offset:1024
	ds_read_b128 v[198:201], v165 offset:2048
	ds_read_b128 v[202:205], v165 offset:3072
	ds_read_b128 v[206:209], v165 offset:4096
	ds_read_b128 v[210:213], v165 offset:5120
	ds_read_b128 v[214:217], v165 offset:6144
	ds_read_b128 v[236:239], v165 offset:7168
	global_load_lds_dwordx4 v[160:161], off
	v_lshl_add_u64 v[160:161], s[56:57], 0, v[140:141]
	s_add_i32 m0, s2, 0xe000
	s_nop 0
	global_load_lds_dwordx4 v[160:161], off
	s_waitcnt vmcnt(8)
	s_waitcnt lgkmcnt(0)
	s_barrier
	s_setprio 1
	s_waitcnt lgkmcnt(0)
	v_mfma_f32_16x16x32_bf16 v[130:133], v[144:147], v[182:185], v[130:133]
	v_mfma_f32_16x16x32_bf16 v[126:129], v[152:155], v[182:185], v[126:129]
	v_mfma_f32_16x16x32_bf16 v[114:117], v[144:147], v[198:201], v[114:117]
	v_mfma_f32_16x16x32_bf16 v[110:113], v[152:155], v[198:201], v[110:113]
	v_mfma_f32_16x16x32_bf16 v[98:101], v[144:147], v[206:209], v[98:101]
	v_mfma_f32_16x16x32_bf16 v[94:97], v[152:155], v[206:209], v[94:97]
	v_mfma_f32_16x16x32_bf16 v[82:85], v[144:147], v[214:217], v[82:85]
	v_mfma_f32_16x16x32_bf16 v[78:81], v[152:155], v[214:217], v[78:81]
	v_mfma_f32_16x16x32_bf16 v[130:133], v[148:151], v[186:189], v[130:133]
	v_mfma_f32_16x16x32_bf16 v[126:129], v[156:159], v[186:189], v[126:129]
	v_mfma_f32_16x16x32_bf16 v[114:117], v[148:151], v[202:205], v[114:117]
	v_mfma_f32_16x16x32_bf16 v[110:113], v[156:159], v[202:205], v[110:113]
	v_mfma_f32_16x16x32_bf16 v[98:101], v[148:151], v[210:213], v[98:101]
	v_mfma_f32_16x16x32_bf16 v[94:97], v[156:159], v[210:213], v[94:97]
	v_mfma_f32_16x16x32_bf16 v[82:85], v[148:151], v[236:239], v[82:85]
	v_mfma_f32_16x16x32_bf16 v[78:81], v[156:159], v[236:239], v[78:81]
	v_mfma_f32_16x16x32_bf16 v[122:125], v[166:169], v[182:185], v[122:125]
	v_mfma_f32_16x16x32_bf16 v[118:121], v[174:177], v[182:185], v[118:121]
	v_mfma_f32_16x16x32_bf16 v[106:109], v[166:169], v[198:201], v[106:109]
	v_mfma_f32_16x16x32_bf16 v[102:105], v[174:177], v[198:201], v[102:105]
	v_mfma_f32_16x16x32_bf16 v[90:93], v[166:169], v[206:209], v[90:93]
	v_mfma_f32_16x16x32_bf16 v[86:89], v[174:177], v[206:209], v[86:89]
	v_mfma_f32_16x16x32_bf16 v[74:77], v[166:169], v[214:217], v[74:77]
	v_mfma_f32_16x16x32_bf16 v[70:73], v[174:177], v[214:217], v[70:73]
	v_mfma_f32_16x16x32_bf16 v[122:125], v[170:173], v[186:189], v[122:125]
	v_mfma_f32_16x16x32_bf16 v[118:121], v[178:181], v[186:189], v[118:121]
	v_mfma_f32_16x16x32_bf16 v[106:109], v[170:173], v[202:205], v[106:109]
	v_mfma_f32_16x16x32_bf16 v[102:105], v[178:181], v[202:205], v[102:105]
	v_mfma_f32_16x16x32_bf16 v[90:93], v[170:173], v[210:213], v[90:93]
	v_mfma_f32_16x16x32_bf16 v[86:89], v[178:181], v[210:213], v[86:89]
	v_mfma_f32_16x16x32_bf16 v[74:77], v[170:173], v[236:239], v[74:77]
	v_mfma_f32_16x16x32_bf16 v[70:73], v[178:181], v[236:239], v[70:73]
	s_setprio 0
	s_barrier
	s_add_i32 s65, s65, s0
	v_lshl_add_u64 v[160:161], s[58:59], 0, v[190:191]
	s_mov_b32 m0, s65
	ds_read_b128 v[182:185], v165 offset:16384
	ds_read_b128 v[186:189], v165 offset:17408
	ds_read_b128 v[198:201], v165 offset:18432
	ds_read_b128 v[202:205], v165 offset:19456
	ds_read_b128 v[206:209], v165 offset:20480
	ds_read_b128 v[210:213], v165 offset:21504
	ds_read_b128 v[214:217], v165 offset:22528
	ds_read_b128 v[236:239], v165 offset:23552
	global_load_lds_dwordx4 v[160:161], off
	s_add_i32 m0, s65, 0x2000
	s_add_u32 s66, s58, 0x80000
	v_lshl_add_u64 v[218:219], s[58:59], 0, v[134:135]
	s_addc_u32 s67, s59, 0
	s_add_i32 s65, s68, s0
	global_load_lds_dwordx4 v[218:219], off
	v_lshl_add_u64 v[240:241], s[66:67], 0, v[190:191]
	s_mov_b32 m0, s65
	v_lshl_add_u64 v[242:243], s[60:61], 0, v[136:137]
	global_load_lds_dwordx4 v[240:241], off
	v_lshl_add_u64 v[240:241], s[66:67], 0, v[134:135]
	s_add_i32 m0, s65, 0x2000
	s_nop 0
	global_load_lds_dwordx4 v[240:241], off
	v_lshl_add_u64 v[240:241], s[60:61], 0, v[138:139]
	s_mov_b32 m0, s2
	s_nop 0
	global_load_lds_dwordx4 v[240:241], off
	s_mov_b32 m0, s3
	s_nop 0
	global_load_lds_dwordx4 v[242:243], off
	s_waitcnt vmcnt(8)
	s_waitcnt lgkmcnt(0)
	s_barrier
	s_setprio 1
	s_waitcnt lgkmcnt(0)
	v_mfma_f32_16x16x32_bf16 v[66:69], v[144:147], v[182:185], v[66:69]
	v_mfma_f32_16x16x32_bf16 v[62:65], v[152:155], v[182:185], v[62:65]
	v_mfma_f32_16x16x32_bf16 v[50:53], v[144:147], v[198:201], v[50:53]
	v_mfma_f32_16x16x32_bf16 v[46:49], v[152:155], v[198:201], v[46:49]
	v_mfma_f32_16x16x32_bf16 v[34:37], v[144:147], v[206:209], v[34:37]
	v_mfma_f32_16x16x32_bf16 v[30:33], v[152:155], v[206:209], v[30:33]
	v_mfma_f32_16x16x32_bf16 v[18:21], v[144:147], v[214:217], v[18:21]
	v_mfma_f32_16x16x32_bf16 v[14:17], v[152:155], v[214:217], v[14:17]
	v_mfma_f32_16x16x32_bf16 v[66:69], v[148:151], v[186:189], v[66:69]
	v_mfma_f32_16x16x32_bf16 v[62:65], v[156:159], v[186:189], v[62:65]
	v_mfma_f32_16x16x32_bf16 v[50:53], v[148:151], v[202:205], v[50:53]
	v_mfma_f32_16x16x32_bf16 v[46:49], v[156:159], v[202:205], v[46:49]
	v_mfma_f32_16x16x32_bf16 v[34:37], v[148:151], v[210:213], v[34:37]
	v_mfma_f32_16x16x32_bf16 v[30:33], v[156:159], v[210:213], v[30:33]
	v_mfma_f32_16x16x32_bf16 v[18:21], v[148:151], v[236:239], v[18:21]
	v_mfma_f32_16x16x32_bf16 v[14:17], v[156:159], v[236:239], v[14:17]
	v_mfma_f32_16x16x32_bf16 v[58:61], v[166:169], v[182:185], v[58:61]
	v_mfma_f32_16x16x32_bf16 v[54:57], v[174:177], v[182:185], v[54:57]
	v_mfma_f32_16x16x32_bf16 v[42:45], v[166:169], v[198:201], v[42:45]
	v_mfma_f32_16x16x32_bf16 v[38:41], v[174:177], v[198:201], v[38:41]
	v_mfma_f32_16x16x32_bf16 v[26:29], v[166:169], v[206:209], v[26:29]
	v_mfma_f32_16x16x32_bf16 v[22:25], v[174:177], v[206:209], v[22:25]
	v_mfma_f32_16x16x32_bf16 v[10:13], v[166:169], v[214:217], v[10:13]
	v_mfma_f32_16x16x32_bf16 v[6:9], v[174:177], v[214:217], v[6:9]
	v_mfma_f32_16x16x32_bf16 v[58:61], v[170:173], v[186:189], v[58:61]
	v_mfma_f32_16x16x32_bf16 v[54:57], v[178:181], v[186:189], v[54:57]
	v_mfma_f32_16x16x32_bf16 v[42:45], v[170:173], v[202:205], v[42:45]
	v_mfma_f32_16x16x32_bf16 v[38:41], v[178:181], v[202:205], v[38:41]
	v_mfma_f32_16x16x32_bf16 v[26:29], v[170:173], v[210:213], v[26:29]
	v_mfma_f32_16x16x32_bf16 v[22:25], v[178:181], v[210:213], v[22:25]
	v_mfma_f32_16x16x32_bf16 v[10:13], v[170:173], v[236:239], v[10:13]
	v_mfma_f32_16x16x32_bf16 v[6:9], v[178:181], v[236:239], v[6:9]
	s_setprio 0
	s_barrier
	s_add_i32 s65, 0, 0x18000
	s_add_i32 s66, 0, 0x1c000
	v_add_u32_e32 v156, s65, v163
	v_add_u32_e32 v178, s66, v163
	ds_read_b128 v[144:147], v156
	ds_read_b128 v[148:151], v156 offset:1024
	ds_read_b128 v[152:155], v156 offset:2048
	ds_read_b128 v[156:159], v156 offset:3072
	ds_read_b128 v[166:169], v178
	ds_read_b128 v[170:173], v178 offset:1024
	ds_read_b128 v[174:177], v178 offset:2048
	ds_read_b128 v[178:181], v178 offset:3072
	s_add_u32 s60, s60, 0x80000
	s_addc_u32 s61, s61, 0
	s_mov_b32 m0, s14
	v_lshl_add_u64 v[244:245], s[60:61], 0, v[138:139]
	ds_read_b128 v[182:185], v165 offset:32768
	ds_read_b128 v[186:189], v165 offset:33792
	ds_read_b128 v[198:201], v165 offset:34816
	ds_read_b128 v[202:205], v165 offset:35840
	ds_read_b128 v[206:209], v165 offset:36864
	ds_read_b128 v[210:213], v165 offset:37888
	ds_read_b128 v[214:217], v165 offset:38912
	ds_read_b128 v[236:239], v165 offset:39936
	global_load_lds_dwordx4 v[244:245], off
	v_lshl_add_u64 v[244:245], s[60:61], 0, v[136:137]
	s_mov_b32 m0, s15
	s_nop 0
	global_load_lds_dwordx4 v[244:245], off
	s_waitcnt vmcnt(8)
	s_waitcnt lgkmcnt(0)
	s_barrier
	s_setprio 1
	s_waitcnt lgkmcnt(0)
	v_mfma_f32_16x16x32_bf16 v[130:133], v[144:147], v[182:185], v[130:133]
	v_mfma_f32_16x16x32_bf16 v[126:129], v[152:155], v[182:185], v[126:129]
	v_mfma_f32_16x16x32_bf16 v[114:117], v[144:147], v[198:201], v[114:117]
	v_mfma_f32_16x16x32_bf16 v[110:113], v[152:155], v[198:201], v[110:113]
	v_mfma_f32_16x16x32_bf16 v[98:101], v[144:147], v[206:209], v[98:101]
	v_mfma_f32_16x16x32_bf16 v[94:97], v[152:155], v[206:209], v[94:97]
	v_mfma_f32_16x16x32_bf16 v[82:85], v[144:147], v[214:217], v[82:85]
	v_mfma_f32_16x16x32_bf16 v[78:81], v[152:155], v[214:217], v[78:81]
	v_mfma_f32_16x16x32_bf16 v[130:133], v[148:151], v[186:189], v[130:133]
	v_mfma_f32_16x16x32_bf16 v[126:129], v[156:159], v[186:189], v[126:129]
	v_mfma_f32_16x16x32_bf16 v[114:117], v[148:151], v[202:205], v[114:117]
	v_mfma_f32_16x16x32_bf16 v[110:113], v[156:159], v[202:205], v[110:113]
	v_mfma_f32_16x16x32_bf16 v[98:101], v[148:151], v[210:213], v[98:101]
	v_mfma_f32_16x16x32_bf16 v[94:97], v[156:159], v[210:213], v[94:97]
	v_mfma_f32_16x16x32_bf16 v[82:85], v[148:151], v[236:239], v[82:85]
	v_mfma_f32_16x16x32_bf16 v[78:81], v[156:159], v[236:239], v[78:81]
	v_mfma_f32_16x16x32_bf16 v[122:125], v[166:169], v[182:185], v[122:125]
	v_mfma_f32_16x16x32_bf16 v[118:121], v[174:177], v[182:185], v[118:121]
	v_mfma_f32_16x16x32_bf16 v[106:109], v[166:169], v[198:201], v[106:109]
	v_mfma_f32_16x16x32_bf16 v[102:105], v[174:177], v[198:201], v[102:105]
	v_mfma_f32_16x16x32_bf16 v[90:93], v[166:169], v[206:209], v[90:93]
	v_mfma_f32_16x16x32_bf16 v[86:89], v[174:177], v[206:209], v[86:89]
	v_mfma_f32_16x16x32_bf16 v[74:77], v[166:169], v[214:217], v[74:77]
	v_mfma_f32_16x16x32_bf16 v[70:73], v[174:177], v[214:217], v[70:73]
	v_mfma_f32_16x16x32_bf16 v[122:125], v[170:173], v[186:189], v[122:125]
	v_mfma_f32_16x16x32_bf16 v[118:121], v[178:181], v[186:189], v[118:121]
	v_mfma_f32_16x16x32_bf16 v[106:109], v[170:173], v[202:205], v[106:109]
	v_mfma_f32_16x16x32_bf16 v[102:105], v[178:181], v[202:205], v[102:105]
	v_mfma_f32_16x16x32_bf16 v[90:93], v[170:173], v[210:213], v[90:93]
	v_mfma_f32_16x16x32_bf16 v[86:89], v[178:181], v[210:213], v[86:89]
	v_mfma_f32_16x16x32_bf16 v[74:77], v[170:173], v[236:239], v[74:77]
	v_mfma_f32_16x16x32_bf16 v[70:73], v[178:181], v[236:239], v[70:73]
	s_setprio 0
	s_barrier
	s_add_i32 s60, s65, s0
	v_lshl_add_u64 v[160:161], v[160:161], 0, s[30:31]
	s_mov_b32 m0, s60
	ds_read_b128 v[182:185], v165 offset:49152
	ds_read_b128 v[186:189], v165 offset:50176
	ds_read_b128 v[198:201], v165 offset:51200
	ds_read_b128 v[202:205], v165 offset:52224
	ds_read_b128 v[206:209], v165 offset:53248
	ds_read_b128 v[210:213], v165 offset:54272
	ds_read_b128 v[214:217], v165 offset:55296
	ds_read_b128 v[236:239], v165 offset:56320
	global_load_lds_dwordx4 v[160:161], off
	s_add_i32 m0, s60, 0x2000
	s_add_u32 s58, s58, 0x80080
	v_lshl_add_u64 v[160:161], v[218:219], 0, s[30:31]
	s_addc_u32 s59, s59, 0
	s_add_i32 s60, s66, s0
	global_load_lds_dwordx4 v[160:161], off
	v_lshl_add_u64 v[160:161], s[58:59], 0, v[190:191]
	s_mov_b32 m0, s60
	s_nop 0
	global_load_lds_dwordx4 v[160:161], off
	v_lshl_add_u64 v[160:161], s[58:59], 0, v[134:135]
	s_add_i32 m0, s60, 0x2000
	s_nop 0
	global_load_lds_dwordx4 v[160:161], off
	v_lshl_add_u64 v[160:161], v[240:241], 0, s[30:31]
	s_mov_b32 m0, s21
	s_nop 0
	global_load_lds_dwordx4 v[160:161], off
	v_lshl_add_u64 v[160:161], v[242:243], 0, s[30:31]
	s_mov_b32 m0, s23
	s_nop 0
	global_load_lds_dwordx4 v[160:161], off
	s_waitcnt vmcnt(8)
	s_waitcnt lgkmcnt(0)
	s_barrier
	s_setprio 1
	s_waitcnt lgkmcnt(0)
	v_mfma_f32_16x16x32_bf16 v[66:69], v[144:147], v[182:185], v[66:69]
	v_mfma_f32_16x16x32_bf16 v[62:65], v[152:155], v[182:185], v[62:65]
	v_mfma_f32_16x16x32_bf16 v[50:53], v[144:147], v[198:201], v[50:53]
	v_mfma_f32_16x16x32_bf16 v[46:49], v[152:155], v[198:201], v[46:49]
	v_mfma_f32_16x16x32_bf16 v[34:37], v[144:147], v[206:209], v[34:37]
	v_mfma_f32_16x16x32_bf16 v[30:33], v[152:155], v[206:209], v[30:33]
	v_mfma_f32_16x16x32_bf16 v[18:21], v[144:147], v[214:217], v[18:21]
	v_mfma_f32_16x16x32_bf16 v[14:17], v[152:155], v[214:217], v[14:17]
	v_mfma_f32_16x16x32_bf16 v[66:69], v[148:151], v[186:189], v[66:69]
	v_mfma_f32_16x16x32_bf16 v[62:65], v[156:159], v[186:189], v[62:65]
	v_mfma_f32_16x16x32_bf16 v[50:53], v[148:151], v[202:205], v[50:53]
	v_mfma_f32_16x16x32_bf16 v[46:49], v[156:159], v[202:205], v[46:49]
	v_mfma_f32_16x16x32_bf16 v[34:37], v[148:151], v[210:213], v[34:37]
	v_mfma_f32_16x16x32_bf16 v[30:33], v[156:159], v[210:213], v[30:33]
	v_mfma_f32_16x16x32_bf16 v[18:21], v[148:151], v[236:239], v[18:21]
	v_mfma_f32_16x16x32_bf16 v[14:17], v[156:159], v[236:239], v[14:17]
	v_mfma_f32_16x16x32_bf16 v[58:61], v[166:169], v[182:185], v[58:61]
	v_mfma_f32_16x16x32_bf16 v[54:57], v[174:177], v[182:185], v[54:57]
	v_mfma_f32_16x16x32_bf16 v[42:45], v[166:169], v[198:201], v[42:45]
	v_mfma_f32_16x16x32_bf16 v[38:41], v[174:177], v[198:201], v[38:41]
	v_mfma_f32_16x16x32_bf16 v[26:29], v[166:169], v[206:209], v[26:29]
	v_mfma_f32_16x16x32_bf16 v[22:25], v[174:177], v[206:209], v[22:25]
	v_mfma_f32_16x16x32_bf16 v[10:13], v[166:169], v[214:217], v[10:13]
	v_mfma_f32_16x16x32_bf16 v[6:9], v[174:177], v[214:217], v[6:9]
	v_mfma_f32_16x16x32_bf16 v[58:61], v[170:173], v[186:189], v[58:61]
	v_mfma_f32_16x16x32_bf16 v[54:57], v[178:181], v[186:189], v[54:57]
	v_mfma_f32_16x16x32_bf16 v[42:45], v[170:173], v[202:205], v[42:45]
	v_mfma_f32_16x16x32_bf16 v[38:41], v[178:181], v[202:205], v[38:41]
	v_mfma_f32_16x16x32_bf16 v[26:29], v[170:173], v[210:213], v[26:29]
	v_mfma_f32_16x16x32_bf16 v[22:25], v[178:181], v[210:213], v[22:25]
	v_mfma_f32_16x16x32_bf16 v[10:13], v[170:173], v[236:239], v[10:13]
	v_mfma_f32_16x16x32_bf16 v[6:9], v[178:181], v[236:239], v[6:9]
	s_setprio 0
	s_barrier
	s_add_i32 s64, s64, 2
	s_add_u32 s62, s62, 0x100
	s_addc_u32 s63, s63, 0
	s_add_u32 s56, s56, 0x100
	s_addc_u32 s57, s57, 0
	s_cmp_gt_u32 s64, 29
	s_cbranch_scc0 .LBB0_1054
	s_and_b64 vcc, exec, s[42:43]
	s_cbranch_vccz .LBB0_1057
	s_barrier
